# GEMM K-loops: removed the back-to-back s_setprio 0 / s_setprio 1 pair between the two 16-MFMA blocks of every compute segment (priority stays raised across all 32 MFMAs)
# baseline (speedup 1.0000x reference)
.LBB0_469:
	s_add_u32 s34, s6, 0xfffc0080
	s_addc_u32 s35, s7, -1
	s_add_i32 s58, 0, 0x10000
	s_cmp_eq_u32 s76, 12
	s_cselect_b32 s57, s1, s35
	s_cselect_b32 s56, s13, s34
	s_cselect_b32 s35, s23, s67
	s_cselect_b32 s34, s25, s66
	s_add_i32 s59, 0, 0x14000
	v_add_u32_e32 v40, s58, v178
	v_add_u32_e32 v64, s59, v178
	ds_read_b128 v[24:27], v40
	ds_read_b128 v[28:31], v40 offset:1024
	ds_read_b128 v[36:39], v40 offset:2048
	ds_read_b128 v[40:43], v40 offset:3072
	ds_read_b128 v[158:161], v64
	ds_read_b128 v[162:165], v64 offset:1024
	ds_read_b128 v[166:169], v64 offset:2048
	ds_read_b128 v[170:173], v64 offset:3072
	v_lshl_add_u64 v[174:175], s[6:7], 0, v[156:157]
	s_add_i32 m0, s90, 0xc000
	ds_read_b128 v[180:183], v179
	ds_read_b128 v[184:187], v179 offset:1024
	ds_read_b128 v[196:199], v179 offset:2048
	ds_read_b128 v[200:203], v179 offset:3072
	ds_read_b128 v[204:207], v179 offset:4096
	ds_read_b128 v[208:211], v179 offset:5120
	ds_read_b128 v[212:215], v179 offset:6144
	ds_read_b128 v[216:219], v179 offset:7168
	global_load_lds_dwordx4 v[174:175], off
	v_lshl_add_u64 v[174:175], s[6:7], 0, v[154:155]
	s_add_i32 m0, s90, 0xe000
	s_nop 0
	global_load_lds_dwordx4 v[174:175], off
	s_waitcnt vmcnt(8)
	s_waitcnt lgkmcnt(0)
	s_barrier
	s_setprio 1
	s_waitcnt lgkmcnt(0)
	v_mfma_f32_16x16x32_bf16 v[142:145], v[24:27], v[180:183], v[142:145]
	v_mfma_f32_16x16x32_bf16 v[138:141], v[36:39], v[180:183], v[138:141]
	v_mfma_f32_16x16x32_bf16 v[126:129], v[24:27], v[196:199], v[126:129]
	v_mfma_f32_16x16x32_bf16 v[122:125], v[36:39], v[196:199], v[122:125]
	v_mfma_f32_16x16x32_bf16 v[110:113], v[24:27], v[204:207], v[110:113]
	v_mfma_f32_16x16x32_bf16 v[106:109], v[36:39], v[204:207], v[106:109]
	v_mfma_f32_16x16x32_bf16 v[94:97], v[24:27], v[212:215], v[94:97]
	v_mfma_f32_16x16x32_bf16 v[90:93], v[36:39], v[212:215], v[90:93]
	v_mfma_f32_16x16x32_bf16 v[142:145], v[28:31], v[184:187], v[142:145]
	v_mfma_f32_16x16x32_bf16 v[138:141], v[40:43], v[184:187], v[138:141]
	v_mfma_f32_16x16x32_bf16 v[126:129], v[28:31], v[200:203], v[126:129]
	v_mfma_f32_16x16x32_bf16 v[122:125], v[40:43], v[200:203], v[122:125]
	v_mfma_f32_16x16x32_bf16 v[110:113], v[28:31], v[208:211], v[110:113]
	v_mfma_f32_16x16x32_bf16 v[106:109], v[40:43], v[208:211], v[106:109]
	v_mfma_f32_16x16x32_bf16 v[94:97], v[28:31], v[216:219], v[94:97]
	v_mfma_f32_16x16x32_bf16 v[90:93], v[40:43], v[216:219], v[90:93]
	v_mfma_f32_16x16x32_bf16 v[134:137], v[158:161], v[180:183], v[134:137]
	v_mfma_f32_16x16x32_bf16 v[130:133], v[166:169], v[180:183], v[130:133]
	v_mfma_f32_16x16x32_bf16 v[118:121], v[158:161], v[196:199], v[118:121]
	v_mfma_f32_16x16x32_bf16 v[114:117], v[166:169], v[196:199], v[114:117]
	v_mfma_f32_16x16x32_bf16 v[102:105], v[158:161], v[204:207], v[102:105]
	v_mfma_f32_16x16x32_bf16 v[98:101], v[166:169], v[204:207], v[98:101]
	v_mfma_f32_16x16x32_bf16 v[86:89], v[158:161], v[212:215], v[86:89]
	v_mfma_f32_16x16x32_bf16 v[82:85], v[166:169], v[212:215], v[82:85]
	v_mfma_f32_16x16x32_bf16 v[134:137], v[162:165], v[184:187], v[134:137]
	v_mfma_f32_16x16x32_bf16 v[130:133], v[170:173], v[184:187], v[130:133]
	v_mfma_f32_16x16x32_bf16 v[118:121], v[162:165], v[200:203], v[118:121]
	v_mfma_f32_16x16x32_bf16 v[114:117], v[170:173], v[200:203], v[114:117]
	v_mfma_f32_16x16x32_bf16 v[102:105], v[162:165], v[208:211], v[102:105]
	v_mfma_f32_16x16x32_bf16 v[98:101], v[170:173], v[208:211], v[98:101]
	v_mfma_f32_16x16x32_bf16 v[86:89], v[162:165], v[216:219], v[86:89]
	v_mfma_f32_16x16x32_bf16 v[82:85], v[170:173], v[216:219], v[82:85]
	s_setprio 0
	s_barrier
	s_add_i32 s58, s58, s87
	v_lshl_add_u64 v[174:175], s[34:35], 0, v[148:149]
	s_mov_b32 m0, s58
	ds_read_b128 v[180:183], v179 offset:16384
	ds_read_b128 v[184:187], v179 offset:17408
	ds_read_b128 v[196:199], v179 offset:18432
	ds_read_b128 v[200:203], v179 offset:19456
	ds_read_b128 v[204:207], v179 offset:20480
	ds_read_b128 v[208:211], v179 offset:21504
	ds_read_b128 v[212:215], v179 offset:22528
	ds_read_b128 v[216:219], v179 offset:23552
	global_load_lds_dwordx4 v[174:175], off
	s_add_i32 m0, s58, 0x2000
	s_add_u32 vcc_lo, s34, 0x40000
	v_lshl_add_u64 v[188:189], s[34:35], 0, v[152:153]
	s_addc_u32 vcc_hi, s35, 0
	s_add_i32 s58, s59, s87
	global_load_lds_dwordx4 v[188:189], off
	v_lshl_add_u64 v[220:221], vcc, 0, v[148:149]
	s_mov_b32 m0, s58
	v_lshl_add_u64 v[222:223], s[56:57], 0, v[150:151]
	global_load_lds_dwordx4 v[220:221], off
	v_lshl_add_u64 v[220:221], vcc, 0, v[152:153]
	s_add_i32 m0, s58, 0x2000
	s_nop 0
	global_load_lds_dwordx4 v[220:221], off
	v_lshl_add_u64 v[220:221], s[56:57], 0, v[146:147]
	s_mov_b32 m0, s90
	s_nop 0
	global_load_lds_dwordx4 v[220:221], off
	s_mov_b32 m0, s91
	s_nop 0
	global_load_lds_dwordx4 v[222:223], off
	s_waitcnt vmcnt(8)
	s_waitcnt lgkmcnt(0)
	s_barrier
	s_setprio 1
	s_waitcnt lgkmcnt(0)
	v_mfma_f32_16x16x32_bf16 v[78:81], v[24:27], v[180:183], v[78:81]
	v_mfma_f32_16x16x32_bf16 v[74:77], v[36:39], v[180:183], v[74:77]
	v_mfma_f32_16x16x32_bf16 v[60:63], v[24:27], v[196:199], v[60:63]
	v_mfma_f32_16x16x32_bf16 v[56:59], v[36:39], v[196:199], v[56:59]
	v_mfma_f32_16x16x32_bf16 v[44:47], v[24:27], v[204:207], v[44:47]
	v_mfma_f32_16x16x32_bf16 v[32:35], v[36:39], v[204:207], v[32:35]
	v_mfma_f32_16x16x32_bf16 v[12:15], v[24:27], v[212:215], v[12:15]
	v_mfma_f32_16x16x32_bf16 v[8:11], v[36:39], v[212:215], v[8:11]
	v_mfma_f32_16x16x32_bf16 v[78:81], v[28:31], v[184:187], v[78:81]
	v_mfma_f32_16x16x32_bf16 v[74:77], v[40:43], v[184:187], v[74:77]
	v_mfma_f32_16x16x32_bf16 v[60:63], v[28:31], v[200:203], v[60:63]
	v_mfma_f32_16x16x32_bf16 v[56:59], v[40:43], v[200:203], v[56:59]
	v_mfma_f32_16x16x32_bf16 v[44:47], v[28:31], v[208:211], v[44:47]
	v_mfma_f32_16x16x32_bf16 v[32:35], v[40:43], v[208:211], v[32:35]
	v_mfma_f32_16x16x32_bf16 v[12:15], v[28:31], v[216:219], v[12:15]
	v_mfma_f32_16x16x32_bf16 v[8:11], v[40:43], v[216:219], v[8:11]
	v_mfma_f32_16x16x32_bf16 v[20:23], v[158:161], v[204:207], v[20:23]
	v_mfma_f32_16x16x32_bf16 v[16:19], v[166:169], v[204:207], v[16:19]
	v_mfma_f32_16x16x32_bf16 v[4:7], v[158:161], v[212:215], v[4:7]
	v_mfma_f32_16x16x32_bf16 v[0:3], v[166:169], v[212:215], v[0:3]
	v_mfma_f32_16x16x32_bf16 v[24:27], v[158:161], v[180:183], v[70:73]
	v_mfma_f32_16x16x32_bf16 v[28:31], v[166:169], v[180:183], v[66:69]
	v_mfma_f32_16x16x32_bf16 v[36:39], v[158:161], v[196:199], v[52:55]
	v_mfma_f32_16x16x32_bf16 v[40:43], v[166:169], v[196:199], v[48:51]
	v_mfma_f32_16x16x32_bf16 v[20:23], v[162:165], v[208:211], v[20:23]
	v_mfma_f32_16x16x32_bf16 v[16:19], v[170:173], v[208:211], v[16:19]
	v_mfma_f32_16x16x32_bf16 v[4:7], v[162:165], v[216:219], v[4:7]
	v_mfma_f32_16x16x32_bf16 v[0:3], v[170:173], v[216:219], v[0:3]
	v_mfma_f32_16x16x32_bf16 v[24:27], v[162:165], v[184:187], v[24:27]
	v_mfma_f32_16x16x32_bf16 v[28:31], v[170:173], v[184:187], v[28:31]
	v_mfma_f32_16x16x32_bf16 v[36:39], v[162:165], v[200:203], v[36:39]
	v_mfma_f32_16x16x32_bf16 v[40:43], v[170:173], v[200:203], v[40:43]
	s_setprio 0
	s_barrier
	s_add_i32 s58, 0, 0x18000
	v_add_u32_e32 v64, s58, v178
	s_add_i32 s59, 0, 0x1c000
	ds_read_b128 v[48:51], v64
	ds_read_b128 v[52:55], v64 offset:1024
	ds_read_b128 v[66:69], v64 offset:2048
	ds_read_b128 v[70:73], v64 offset:3072
	v_add_u32_e32 v64, s59, v178
	ds_read_b128 v[158:161], v64
	ds_read_b128 v[162:165], v64 offset:1024
	ds_read_b128 v[166:169], v64 offset:2048
	ds_read_b128 v[170:173], v64 offset:3072
	s_add_u32 s56, s56, 0x40000
	s_addc_u32 s57, s57, 0
	s_mov_b32 m0, s44
	v_lshl_add_u64 v[224:225], s[56:57], 0, v[146:147]
	ds_read_b128 v[180:183], v179 offset:32768
	ds_read_b128 v[184:187], v179 offset:33792
	ds_read_b128 v[196:199], v179 offset:34816
	ds_read_b128 v[200:203], v179 offset:35840
	ds_read_b128 v[204:207], v179 offset:36864
	ds_read_b128 v[208:211], v179 offset:37888
	ds_read_b128 v[212:215], v179 offset:38912
	ds_read_b128 v[216:219], v179 offset:39936
	global_load_lds_dwordx4 v[224:225], off
	v_lshl_add_u64 v[224:225], s[56:57], 0, v[150:151]
	s_mov_b32 m0, s33
	s_nop 0
	global_load_lds_dwordx4 v[224:225], off
	s_waitcnt vmcnt(8)
	s_waitcnt lgkmcnt(0)
	s_barrier
	s_setprio 1
	s_waitcnt lgkmcnt(0)
	v_mfma_f32_16x16x32_bf16 v[142:145], v[48:51], v[180:183], v[142:145]
	v_mfma_f32_16x16x32_bf16 v[138:141], v[66:69], v[180:183], v[138:141]
	v_mfma_f32_16x16x32_bf16 v[126:129], v[48:51], v[196:199], v[126:129]
	v_mfma_f32_16x16x32_bf16 v[122:125], v[66:69], v[196:199], v[122:125]
	v_mfma_f32_16x16x32_bf16 v[110:113], v[48:51], v[204:207], v[110:113]
	v_mfma_f32_16x16x32_bf16 v[106:109], v[66:69], v[204:207], v[106:109]
	v_mfma_f32_16x16x32_bf16 v[94:97], v[48:51], v[212:215], v[94:97]
	v_mfma_f32_16x16x32_bf16 v[90:93], v[66:69], v[212:215], v[90:93]
	v_mfma_f32_16x16x32_bf16 v[142:145], v[52:55], v[184:187], v[142:145]
	v_mfma_f32_16x16x32_bf16 v[138:141], v[70:73], v[184:187], v[138:141]
	v_mfma_f32_16x16x32_bf16 v[126:129], v[52:55], v[200:203], v[126:129]
	v_mfma_f32_16x16x32_bf16 v[122:125], v[70:73], v[200:203], v[122:125]
	v_mfma_f32_16x16x32_bf16 v[110:113], v[52:55], v[208:211], v[110:113]
	v_mfma_f32_16x16x32_bf16 v[106:109], v[70:73], v[208:211], v[106:109]
	v_mfma_f32_16x16x32_bf16 v[94:97], v[52:55], v[216:219], v[94:97]
	v_mfma_f32_16x16x32_bf16 v[90:93], v[70:73], v[216:219], v[90:93]
	v_mfma_f32_16x16x32_bf16 v[134:137], v[158:161], v[180:183], v[134:137]
	v_mfma_f32_16x16x32_bf16 v[130:133], v[166:169], v[180:183], v[130:133]
	v_mfma_f32_16x16x32_bf16 v[118:121], v[158:161], v[196:199], v[118:121]
	v_mfma_f32_16x16x32_bf16 v[114:117], v[166:169], v[196:199], v[114:117]
	v_mfma_f32_16x16x32_bf16 v[102:105], v[158:161], v[204:207], v[102:105]
	v_mfma_f32_16x16x32_bf16 v[98:101], v[166:169], v[204:207], v[98:101]
	v_mfma_f32_16x16x32_bf16 v[86:89], v[158:161], v[212:215], v[86:89]
	v_mfma_f32_16x16x32_bf16 v[82:85], v[166:169], v[212:215], v[82:85]
	v_mfma_f32_16x16x32_bf16 v[134:137], v[162:165], v[184:187], v[134:137]
	v_mfma_f32_16x16x32_bf16 v[130:133], v[170:173], v[184:187], v[130:133]
	v_mfma_f32_16x16x32_bf16 v[118:121], v[162:165], v[200:203], v[118:121]
	v_mfma_f32_16x16x32_bf16 v[114:117], v[170:173], v[200:203], v[114:117]
	v_mfma_f32_16x16x32_bf16 v[102:105], v[162:165], v[208:211], v[102:105]
	v_mfma_f32_16x16x32_bf16 v[98:101], v[170:173], v[208:211], v[98:101]
	v_mfma_f32_16x16x32_bf16 v[86:89], v[162:165], v[216:219], v[86:89]
	v_mfma_f32_16x16x32_bf16 v[82:85], v[170:173], v[216:219], v[82:85]
	s_setprio 0
	s_barrier
	s_add_i32 s56, s58, s87
	v_lshl_add_u64 v[174:175], v[174:175], 0, s[30:31]
	s_mov_b32 m0, s56
	ds_read_b128 v[180:183], v179 offset:49152
	ds_read_b128 v[184:187], v179 offset:50176
	ds_read_b128 v[196:199], v179 offset:51200
	ds_read_b128 v[200:203], v179 offset:52224
	ds_read_b128 v[204:207], v179 offset:53248
	ds_read_b128 v[208:211], v179 offset:54272
	ds_read_b128 v[212:215], v179 offset:55296
	ds_read_b128 v[216:219], v179 offset:56320
	global_load_lds_dwordx4 v[174:175], off
	s_add_i32 m0, s56, 0x2000
	s_add_u32 s34, s34, 0x40080
	v_lshl_add_u64 v[174:175], v[188:189], 0, s[30:31]
	s_addc_u32 s35, s35, 0
	s_add_i32 s56, s59, s87
	global_load_lds_dwordx4 v[174:175], off
	v_lshl_add_u64 v[174:175], s[34:35], 0, v[148:149]
	s_mov_b32 m0, s56
	s_nop 0
	global_load_lds_dwordx4 v[174:175], off
	v_lshl_add_u64 v[174:175], s[34:35], 0, v[152:153]
	s_add_i32 m0, s56, 0x2000
	s_nop 0
	global_load_lds_dwordx4 v[174:175], off
	v_lshl_add_u64 v[174:175], v[220:221], 0, s[30:31]
	s_mov_b32 m0, s88
	s_nop 0
	global_load_lds_dwordx4 v[174:175], off
	v_lshl_add_u64 v[174:175], v[222:223], 0, s[30:31]
	s_mov_b32 m0, s89
	s_nop 0
	global_load_lds_dwordx4 v[174:175], off
	s_waitcnt vmcnt(8)
	s_waitcnt lgkmcnt(0)
	s_barrier
	s_setprio 1
	s_waitcnt lgkmcnt(0)
	v_mfma_f32_16x16x32_bf16 v[78:81], v[48:51], v[180:183], v[78:81]
	v_mfma_f32_16x16x32_bf16 v[74:77], v[66:69], v[180:183], v[74:77]
	v_mfma_f32_16x16x32_bf16 v[60:63], v[48:51], v[196:199], v[60:63]
	v_mfma_f32_16x16x32_bf16 v[56:59], v[66:69], v[196:199], v[56:59]
	v_mfma_f32_16x16x32_bf16 v[44:47], v[48:51], v[204:207], v[44:47]
	v_mfma_f32_16x16x32_bf16 v[32:35], v[66:69], v[204:207], v[32:35]
	v_mfma_f32_16x16x32_bf16 v[12:15], v[48:51], v[212:215], v[12:15]
	v_mfma_f32_16x16x32_bf16 v[8:11], v[66:69], v[212:215], v[8:11]
	v_mfma_f32_16x16x32_bf16 v[78:81], v[52:55], v[184:187], v[78:81]
	v_mfma_f32_16x16x32_bf16 v[74:77], v[70:73], v[184:187], v[74:77]
	v_mfma_f32_16x16x32_bf16 v[60:63], v[52:55], v[200:203], v[60:63]
	v_mfma_f32_16x16x32_bf16 v[56:59], v[70:73], v[200:203], v[56:59]
	v_mfma_f32_16x16x32_bf16 v[44:47], v[52:55], v[208:211], v[44:47]
	v_mfma_f32_16x16x32_bf16 v[32:35], v[70:73], v[208:211], v[32:35]
	v_mfma_f32_16x16x32_bf16 v[12:15], v[52:55], v[216:219], v[12:15]
	v_mfma_f32_16x16x32_bf16 v[8:11], v[70:73], v[216:219], v[8:11]
	v_mfma_f32_16x16x32_bf16 v[24:27], v[158:161], v[180:183], v[24:27]
	v_mfma_f32_16x16x32_bf16 v[70:73], v[162:165], v[184:187], v[24:27]
	v_mfma_f32_16x16x32_bf16 v[24:27], v[166:169], v[180:183], v[28:31]
	v_mfma_f32_16x16x32_bf16 v[66:69], v[170:173], v[184:187], v[24:27]
	v_mfma_f32_16x16x32_bf16 v[24:27], v[158:161], v[196:199], v[36:39]
	v_mfma_f32_16x16x32_bf16 v[52:55], v[162:165], v[200:203], v[24:27]
	v_mfma_f32_16x16x32_bf16 v[24:27], v[166:169], v[196:199], v[40:43]
	v_mfma_f32_16x16x32_bf16 v[20:23], v[158:161], v[204:207], v[20:23]
	v_mfma_f32_16x16x32_bf16 v[16:19], v[166:169], v[204:207], v[16:19]
	v_mfma_f32_16x16x32_bf16 v[4:7], v[158:161], v[212:215], v[4:7]
	v_mfma_f32_16x16x32_bf16 v[0:3], v[166:169], v[212:215], v[0:3]
	v_mfma_f32_16x16x32_bf16 v[48:51], v[170:173], v[200:203], v[24:27]
	v_mfma_f32_16x16x32_bf16 v[20:23], v[162:165], v[208:211], v[20:23]
	v_mfma_f32_16x16x32_bf16 v[16:19], v[170:173], v[208:211], v[16:19]
	v_mfma_f32_16x16x32_bf16 v[4:7], v[162:165], v[216:219], v[4:7]
	v_mfma_f32_16x16x32_bf16 v[0:3], v[170:173], v[216:219], v[0:3]
	s_setprio 0
	s_barrier
	s_add_i32 s76, s76, 2
	s_add_u32 s66, s66, 0x100
	s_addc_u32 s67, s67, 0
	s_add_u32 s6, s6, 0x100
	s_addc_u32 s7, s7, 0
	s_cmp_gt_u32 s76, 13
	s_cbranch_scc0 .LBB0_469
	s_and_b64 vcc, exec, s[20:21]
	s_cbranch_vccz .LBB0_472
	s_barrier

.LBB0_1826:
	s_add_u32 s12, s35, s10
	s_addc_u32 s13, s44, s11
	s_add_u32 s12, s12, 0x9600100
	s_addc_u32 s13, s13, 0
	s_add_u32 s56, s33, s10
	s_addc_u32 s57, s34, s11
	s_add_i32 s58, 0, 0x10000
	s_cmpk_eq_i32 s10, 0x700
	s_cselect_b32 s15, s9, s13
	s_cselect_b32 s14, s8, s12
	s_cselect_b32 s13, s1, s57
	s_cselect_b32 s12, s0, s56
	s_add_i32 s59, 0, 0x14000
	v_add_u32_e32 v156, s58, v58
	v_add_u32_e32 v172, s59, v58
	ds_read_b128 v[60:63], v156
	ds_read_b128 v[148:151], v156 offset:1024
	ds_read_b128 v[152:155], v156 offset:2048
	ds_read_b128 v[156:159], v156 offset:3072
	ds_read_b128 v[160:163], v172
	ds_read_b128 v[164:167], v172 offset:1024
	ds_read_b128 v[168:171], v172 offset:2048
	ds_read_b128 v[172:175], v172 offset:3072
	v_lshl_add_u64 v[188:189], v[56:57], 0, s[10:11]
	s_add_i32 m0, s19, 0xc000
	ds_read_b128 v[176:179], v59
	ds_read_b128 v[180:183], v59 offset:1024
	ds_read_b128 v[184:187], v59 offset:2048
	ds_read_b128 v[198:201], v59 offset:3072
	ds_read_b128 v[202:205], v59 offset:4096
	ds_read_b128 v[206:209], v59 offset:5120
	ds_read_b128 v[210:213], v59 offset:6144
	ds_read_b128 v[214:217], v59 offset:7168
	global_load_lds_dwordx4 v[188:189], off
	v_lshl_add_u64 v[188:189], v[50:51], 0, s[10:11]
	s_add_i32 m0, s19, 0xe000
	s_nop 0
	global_load_lds_dwordx4 v[188:189], off
	s_waitcnt vmcnt(8)
	s_waitcnt lgkmcnt(0)
	s_barrier
	s_setprio 1
	s_waitcnt lgkmcnt(0)
	v_mfma_f32_16x16x32_bf16 v[142:145], v[60:63], v[176:179], v[142:145]
	v_mfma_f32_16x16x32_bf16 v[138:141], v[152:155], v[176:179], v[138:141]
	v_mfma_f32_16x16x32_bf16 v[126:129], v[60:63], v[184:187], v[126:129]
	v_mfma_f32_16x16x32_bf16 v[122:125], v[152:155], v[184:187], v[122:125]
	v_mfma_f32_16x16x32_bf16 v[110:113], v[60:63], v[202:205], v[110:113]
	v_mfma_f32_16x16x32_bf16 v[106:109], v[152:155], v[202:205], v[106:109]
	v_mfma_f32_16x16x32_bf16 v[94:97], v[60:63], v[210:213], v[94:97]
	v_mfma_f32_16x16x32_bf16 v[90:93], v[152:155], v[210:213], v[90:93]
	v_mfma_f32_16x16x32_bf16 v[142:145], v[148:151], v[180:183], v[142:145]
	v_mfma_f32_16x16x32_bf16 v[138:141], v[156:159], v[180:183], v[138:141]
	v_mfma_f32_16x16x32_bf16 v[126:129], v[148:151], v[198:201], v[126:129]
	v_mfma_f32_16x16x32_bf16 v[122:125], v[156:159], v[198:201], v[122:125]
	v_mfma_f32_16x16x32_bf16 v[110:113], v[148:151], v[206:209], v[110:113]
	v_mfma_f32_16x16x32_bf16 v[106:109], v[156:159], v[206:209], v[106:109]
	v_mfma_f32_16x16x32_bf16 v[94:97], v[148:151], v[214:217], v[94:97]
	v_mfma_f32_16x16x32_bf16 v[90:93], v[156:159], v[214:217], v[90:93]
	v_mfma_f32_16x16x32_bf16 v[134:137], v[160:163], v[176:179], v[134:137]
	v_mfma_f32_16x16x32_bf16 v[130:133], v[168:171], v[176:179], v[130:133]
	v_mfma_f32_16x16x32_bf16 v[118:121], v[160:163], v[184:187], v[118:121]
	v_mfma_f32_16x16x32_bf16 v[114:117], v[168:171], v[184:187], v[114:117]
	v_mfma_f32_16x16x32_bf16 v[102:105], v[160:163], v[202:205], v[102:105]
	v_mfma_f32_16x16x32_bf16 v[98:101], v[168:171], v[202:205], v[98:101]
	v_mfma_f32_16x16x32_bf16 v[86:89], v[160:163], v[210:213], v[86:89]
	v_mfma_f32_16x16x32_bf16 v[82:85], v[168:171], v[210:213], v[82:85]
	v_mfma_f32_16x16x32_bf16 v[134:137], v[164:167], v[180:183], v[134:137]
	v_mfma_f32_16x16x32_bf16 v[130:133], v[172:175], v[180:183], v[130:133]
	v_mfma_f32_16x16x32_bf16 v[118:121], v[164:167], v[198:201], v[118:121]
	v_mfma_f32_16x16x32_bf16 v[114:117], v[172:175], v[198:201], v[114:117]
	v_mfma_f32_16x16x32_bf16 v[102:105], v[164:167], v[206:209], v[102:105]
	v_mfma_f32_16x16x32_bf16 v[98:101], v[172:175], v[206:209], v[98:101]
	v_mfma_f32_16x16x32_bf16 v[86:89], v[164:167], v[214:217], v[86:89]
	v_mfma_f32_16x16x32_bf16 v[82:85], v[172:175], v[214:217], v[82:85]
	s_setprio 0
	s_barrier
	s_add_i32 s56, s58, s18
	v_lshl_add_u64 v[188:189], s[12:13], 0, v[44:45]
	s_mov_b32 m0, s56
	ds_read_b128 v[176:179], v59 offset:16384
	ds_read_b128 v[180:183], v59 offset:17408
	ds_read_b128 v[184:187], v59 offset:18432
	ds_read_b128 v[198:201], v59 offset:19456
	ds_read_b128 v[202:205], v59 offset:20480
	ds_read_b128 v[206:209], v59 offset:21504
	ds_read_b128 v[210:213], v59 offset:22528
	ds_read_b128 v[214:217], v59 offset:23552
	global_load_lds_dwordx4 v[188:189], off
	s_add_i32 m0, s56, 0x2000
	s_add_u32 s56, s12, 0x40000
	v_lshl_add_u64 v[218:219], s[12:13], 0, v[48:49]
	s_addc_u32 s57, s13, 0
	s_add_i32 s58, s59, s18
	global_load_lds_dwordx4 v[218:219], off
	v_lshl_add_u64 v[220:221], s[56:57], 0, v[44:45]
	s_mov_b32 m0, s58
	v_lshl_add_u64 v[222:223], s[14:15], 0, v[46:47]
	global_load_lds_dwordx4 v[220:221], off
	v_lshl_add_u64 v[220:221], s[56:57], 0, v[48:49]
	s_add_i32 m0, s58, 0x2000
	s_nop 0
	global_load_lds_dwordx4 v[220:221], off
	v_lshl_add_u64 v[220:221], s[14:15], 0, v[64:65]
	s_mov_b32 m0, s19
	s_nop 0
	global_load_lds_dwordx4 v[220:221], off
	s_mov_b32 m0, s20
	s_nop 0
	global_load_lds_dwordx4 v[222:223], off
	s_waitcnt vmcnt(8)
	s_waitcnt lgkmcnt(0)
	s_barrier
	s_setprio 1
	s_waitcnt lgkmcnt(0)
	v_mfma_f32_16x16x32_bf16 v[78:81], v[60:63], v[176:179], v[78:81]
	v_mfma_f32_16x16x32_bf16 v[74:77], v[152:155], v[176:179], v[74:77]
	v_mfma_f32_16x16x32_bf16 v[52:55], v[60:63], v[184:187], v[52:55]
	v_mfma_f32_16x16x32_bf16 v[40:43], v[152:155], v[184:187], v[40:43]
	v_mfma_f32_16x16x32_bf16 v[28:31], v[60:63], v[202:205], v[28:31]
	v_mfma_f32_16x16x32_bf16 v[24:27], v[152:155], v[202:205], v[24:27]
	v_mfma_f32_16x16x32_bf16 v[12:15], v[60:63], v[210:213], v[12:15]
	v_mfma_f32_16x16x32_bf16 v[8:11], v[152:155], v[210:213], v[8:11]
	v_mfma_f32_16x16x32_bf16 v[78:81], v[148:151], v[180:183], v[78:81]
	v_mfma_f32_16x16x32_bf16 v[74:77], v[156:159], v[180:183], v[74:77]
	v_mfma_f32_16x16x32_bf16 v[52:55], v[148:151], v[198:201], v[52:55]
	v_mfma_f32_16x16x32_bf16 v[40:43], v[156:159], v[198:201], v[40:43]
	v_mfma_f32_16x16x32_bf16 v[28:31], v[148:151], v[206:209], v[28:31]
	v_mfma_f32_16x16x32_bf16 v[24:27], v[156:159], v[206:209], v[24:27]
	v_mfma_f32_16x16x32_bf16 v[12:15], v[148:151], v[214:217], v[12:15]
	v_mfma_f32_16x16x32_bf16 v[8:11], v[156:159], v[214:217], v[8:11]
	v_mfma_f32_16x16x32_bf16 v[66:69], v[168:171], v[176:179], v[66:69]
	v_mfma_f32_16x16x32_bf16 v[36:39], v[160:163], v[184:187], v[36:39]
	v_mfma_f32_16x16x32_bf16 v[32:35], v[168:171], v[184:187], v[32:35]
	v_mfma_f32_16x16x32_bf16 v[20:23], v[160:163], v[202:205], v[20:23]
	v_mfma_f32_16x16x32_bf16 v[16:19], v[168:171], v[202:205], v[16:19]
	v_mfma_f32_16x16x32_bf16 v[4:7], v[160:163], v[210:213], v[4:7]
	v_mfma_f32_16x16x32_bf16 v[0:3], v[168:171], v[210:213], v[0:3]
	v_mfma_f32_16x16x32_bf16 v[60:63], v[160:163], v[176:179], v[70:73]
	v_mfma_f32_16x16x32_bf16 v[66:69], v[172:175], v[180:183], v[66:69]
	v_mfma_f32_16x16x32_bf16 v[36:39], v[164:167], v[198:201], v[36:39]
	v_mfma_f32_16x16x32_bf16 v[32:35], v[172:175], v[198:201], v[32:35]
	v_mfma_f32_16x16x32_bf16 v[20:23], v[164:167], v[206:209], v[20:23]
	v_mfma_f32_16x16x32_bf16 v[16:19], v[172:175], v[206:209], v[16:19]
	v_mfma_f32_16x16x32_bf16 v[4:7], v[164:167], v[214:217], v[4:7]
	v_mfma_f32_16x16x32_bf16 v[0:3], v[172:175], v[214:217], v[0:3]
	v_mfma_f32_16x16x32_bf16 v[60:63], v[164:167], v[180:183], v[60:63]
	s_setprio 0
	s_barrier
	s_add_i32 s56, 0, 0x18000
	s_add_i32 s57, 0, 0x1c000
	v_add_u32_e32 v156, s56, v58
	v_add_u32_e32 v172, s57, v58
	ds_read_b128 v[70:73], v156
	ds_read_b128 v[148:151], v156 offset:1024
	ds_read_b128 v[152:155], v156 offset:2048
	ds_read_b128 v[156:159], v156 offset:3072
	ds_read_b128 v[160:163], v172
	ds_read_b128 v[164:167], v172 offset:1024
	ds_read_b128 v[168:171], v172 offset:2048
	ds_read_b128 v[172:175], v172 offset:3072
	s_add_u32 s14, s14, 0x40000
	s_addc_u32 s15, s15, 0
	s_mov_b32 m0, s21
	v_lshl_add_u64 v[224:225], s[14:15], 0, v[64:65]
	ds_read_b128 v[176:179], v59 offset:32768
	ds_read_b128 v[180:183], v59 offset:33792
	ds_read_b128 v[184:187], v59 offset:34816
	ds_read_b128 v[198:201], v59 offset:35840
	ds_read_b128 v[202:205], v59 offset:36864
	ds_read_b128 v[206:209], v59 offset:37888
	ds_read_b128 v[210:213], v59 offset:38912
	ds_read_b128 v[214:217], v59 offset:39936
	global_load_lds_dwordx4 v[224:225], off
	v_lshl_add_u64 v[224:225], s[14:15], 0, v[46:47]
	s_mov_b32 m0, s23
	s_nop 0
	global_load_lds_dwordx4 v[224:225], off
	s_waitcnt vmcnt(8)
	s_waitcnt lgkmcnt(0)
	s_barrier
	s_setprio 1
	s_waitcnt lgkmcnt(0)
	v_mfma_f32_16x16x32_bf16 v[142:145], v[70:73], v[176:179], v[142:145]
	v_mfma_f32_16x16x32_bf16 v[138:141], v[152:155], v[176:179], v[138:141]
	v_mfma_f32_16x16x32_bf16 v[126:129], v[70:73], v[184:187], v[126:129]
	v_mfma_f32_16x16x32_bf16 v[122:125], v[152:155], v[184:187], v[122:125]
	v_mfma_f32_16x16x32_bf16 v[110:113], v[70:73], v[202:205], v[110:113]
	v_mfma_f32_16x16x32_bf16 v[106:109], v[152:155], v[202:205], v[106:109]
	v_mfma_f32_16x16x32_bf16 v[94:97], v[70:73], v[210:213], v[94:97]
	v_mfma_f32_16x16x32_bf16 v[90:93], v[152:155], v[210:213], v[90:93]
	v_mfma_f32_16x16x32_bf16 v[142:145], v[148:151], v[180:183], v[142:145]
	v_mfma_f32_16x16x32_bf16 v[138:141], v[156:159], v[180:183], v[138:141]
	v_mfma_f32_16x16x32_bf16 v[126:129], v[148:151], v[198:201], v[126:129]
	v_mfma_f32_16x16x32_bf16 v[122:125], v[156:159], v[198:201], v[122:125]
	v_mfma_f32_16x16x32_bf16 v[110:113], v[148:151], v[206:209], v[110:113]
	v_mfma_f32_16x16x32_bf16 v[106:109], v[156:159], v[206:209], v[106:109]
	v_mfma_f32_16x16x32_bf16 v[94:97], v[148:151], v[214:217], v[94:97]
	v_mfma_f32_16x16x32_bf16 v[90:93], v[156:159], v[214:217], v[90:93]
	v_mfma_f32_16x16x32_bf16 v[134:137], v[160:163], v[176:179], v[134:137]
	v_mfma_f32_16x16x32_bf16 v[130:133], v[168:171], v[176:179], v[130:133]
	v_mfma_f32_16x16x32_bf16 v[118:121], v[160:163], v[184:187], v[118:121]
	v_mfma_f32_16x16x32_bf16 v[114:117], v[168:171], v[184:187], v[114:117]
	v_mfma_f32_16x16x32_bf16 v[102:105], v[160:163], v[202:205], v[102:105]
	v_mfma_f32_16x16x32_bf16 v[98:101], v[168:171], v[202:205], v[98:101]
	v_mfma_f32_16x16x32_bf16 v[86:89], v[160:163], v[210:213], v[86:89]
	v_mfma_f32_16x16x32_bf16 v[82:85], v[168:171], v[210:213], v[82:85]
	v_mfma_f32_16x16x32_bf16 v[134:137], v[164:167], v[180:183], v[134:137]
	v_mfma_f32_16x16x32_bf16 v[130:133], v[172:175], v[180:183], v[130:133]
	v_mfma_f32_16x16x32_bf16 v[118:121], v[164:167], v[198:201], v[118:121]
	v_mfma_f32_16x16x32_bf16 v[114:117], v[172:175], v[198:201], v[114:117]
	v_mfma_f32_16x16x32_bf16 v[102:105], v[164:167], v[206:209], v[102:105]
	v_mfma_f32_16x16x32_bf16 v[98:101], v[172:175], v[206:209], v[98:101]
	v_mfma_f32_16x16x32_bf16 v[86:89], v[164:167], v[214:217], v[86:89]
	v_mfma_f32_16x16x32_bf16 v[82:85], v[172:175], v[214:217], v[82:85]
	s_setprio 0
	s_barrier
	s_add_i32 s14, s56, s18
	v_lshl_add_u64 v[188:189], v[188:189], 0, s[30:31]
	s_mov_b32 m0, s14
	ds_read_b128 v[176:179], v59 offset:49152
	ds_read_b128 v[180:183], v59 offset:50176
	ds_read_b128 v[184:187], v59 offset:51200
	ds_read_b128 v[198:201], v59 offset:52224
	ds_read_b128 v[202:205], v59 offset:53248
	ds_read_b128 v[206:209], v59 offset:54272
	ds_read_b128 v[210:213], v59 offset:55296
	ds_read_b128 v[214:217], v59 offset:56320
	global_load_lds_dwordx4 v[188:189], off
	s_add_i32 m0, s14, 0x2000
	s_add_u32 s12, s12, 0x40080
	v_lshl_add_u64 v[188:189], v[218:219], 0, s[30:31]
	s_addc_u32 s13, s13, 0
	s_add_i32 s14, s57, s18
	global_load_lds_dwordx4 v[188:189], off
	v_lshl_add_u64 v[188:189], s[12:13], 0, v[44:45]
	s_mov_b32 m0, s14
	s_nop 0
	global_load_lds_dwordx4 v[188:189], off
	v_lshl_add_u64 v[188:189], s[12:13], 0, v[48:49]
	s_add_i32 m0, s14, 0x2000
	s_nop 0
	global_load_lds_dwordx4 v[188:189], off
	v_lshl_add_u64 v[188:189], v[220:221], 0, s[30:31]
	s_mov_b32 m0, s24
	s_nop 0
	global_load_lds_dwordx4 v[188:189], off
	v_lshl_add_u64 v[188:189], v[222:223], 0, s[30:31]
	s_mov_b32 m0, s25
	s_nop 0
	global_load_lds_dwordx4 v[188:189], off
	s_waitcnt vmcnt(8)
	s_waitcnt lgkmcnt(0)
	s_barrier
	s_setprio 1
	s_waitcnt lgkmcnt(0)
	v_mfma_f32_16x16x32_bf16 v[78:81], v[70:73], v[176:179], v[78:81]
	v_mfma_f32_16x16x32_bf16 v[74:77], v[152:155], v[176:179], v[74:77]
	v_mfma_f32_16x16x32_bf16 v[52:55], v[70:73], v[184:187], v[52:55]
	v_mfma_f32_16x16x32_bf16 v[40:43], v[152:155], v[184:187], v[40:43]
	v_mfma_f32_16x16x32_bf16 v[28:31], v[70:73], v[202:205], v[28:31]
	v_mfma_f32_16x16x32_bf16 v[24:27], v[152:155], v[202:205], v[24:27]
	v_mfma_f32_16x16x32_bf16 v[12:15], v[70:73], v[210:213], v[12:15]
	v_mfma_f32_16x16x32_bf16 v[8:11], v[152:155], v[210:213], v[8:11]
	v_mfma_f32_16x16x32_bf16 v[78:81], v[148:151], v[180:183], v[78:81]
	v_mfma_f32_16x16x32_bf16 v[74:77], v[156:159], v[180:183], v[74:77]
	v_mfma_f32_16x16x32_bf16 v[52:55], v[148:151], v[198:201], v[52:55]
	v_mfma_f32_16x16x32_bf16 v[40:43], v[156:159], v[198:201], v[40:43]
	v_mfma_f32_16x16x32_bf16 v[28:31], v[148:151], v[206:209], v[28:31]
	v_mfma_f32_16x16x32_bf16 v[24:27], v[156:159], v[206:209], v[24:27]
	v_mfma_f32_16x16x32_bf16 v[12:15], v[148:151], v[214:217], v[12:15]
	v_mfma_f32_16x16x32_bf16 v[8:11], v[156:159], v[214:217], v[8:11]
	v_mfma_f32_16x16x32_bf16 v[60:63], v[160:163], v[176:179], v[60:63]
	v_mfma_f32_16x16x32_bf16 v[70:73], v[164:167], v[180:183], v[60:63]
	v_mfma_f32_16x16x32_bf16 v[60:63], v[168:171], v[176:179], v[66:69]
	v_mfma_f32_16x16x32_bf16 v[36:39], v[160:163], v[184:187], v[36:39]
	v_mfma_f32_16x16x32_bf16 v[32:35], v[168:171], v[184:187], v[32:35]
	v_mfma_f32_16x16x32_bf16 v[20:23], v[160:163], v[202:205], v[20:23]
	v_mfma_f32_16x16x32_bf16 v[16:19], v[168:171], v[202:205], v[16:19]
	v_mfma_f32_16x16x32_bf16 v[4:7], v[160:163], v[210:213], v[4:7]
	v_mfma_f32_16x16x32_bf16 v[0:3], v[168:171], v[210:213], v[0:3]
	v_mfma_f32_16x16x32_bf16 v[66:69], v[172:175], v[180:183], v[60:63]
	v_mfma_f32_16x16x32_bf16 v[36:39], v[164:167], v[198:201], v[36:39]
	v_mfma_f32_16x16x32_bf16 v[32:35], v[172:175], v[198:201], v[32:35]
	v_mfma_f32_16x16x32_bf16 v[20:23], v[164:167], v[206:209], v[20:23]
	v_mfma_f32_16x16x32_bf16 v[16:19], v[172:175], v[206:209], v[16:19]
	v_mfma_f32_16x16x32_bf16 v[4:7], v[164:167], v[214:217], v[4:7]
	v_mfma_f32_16x16x32_bf16 v[0:3], v[172:175], v[214:217], v[0:3]
	s_setprio 0
	s_barrier
	s_add_i32 s53, s53, 2
	s_add_u32 s10, s10, 0x100
	s_addc_u32 s11, s11, 0
	s_cmp_gt_u32 s53, 13
	s_cbranch_scc0 .LBB0_1826
	s_cmpk_lt_u32 s16, 0x100
	s_cbranch_scc0 .LBB0_1829
	s_barrier

.LBB0_1884:
	s_add_u32 s0, s56, 0xfffc0080
	s_addc_u32 s1, s57, -1
	s_add_i32 s58, 0, 0x10000
	s_cmp_eq_u32 vcc_lo, 12
	s_cselect_b32 s83, s9, s1
	s_cselect_b32 s82, s25, s0
	s_cselect_b32 s35, s23, s96
	s_cselect_b32 s34, s66, s67
	s_add_i32 s59, 0, 0x14000
	v_add_u32_e32 v70, s58, v227
	v_add_u32_e32 v86, s59, v227
	ds_read_b128 v[56:59], v70
	ds_read_b128 v[60:63], v70 offset:1024
	ds_read_b128 v[66:69], v70 offset:2048
	ds_read_b128 v[70:73], v70 offset:3072
	ds_read_b128 v[74:77], v86
	ds_read_b128 v[78:81], v86 offset:1024
	ds_read_b128 v[82:85], v86 offset:2048
	ds_read_b128 v[86:89], v86 offset:3072
	v_lshl_add_u64 v[210:211], s[56:57], 0, v[204:205]
	s_add_i32 m0, s53, 0xc000
	ds_read_b128 v[162:165], v240
	ds_read_b128 v[166:169], v240 offset:1024
	ds_read_b128 v[170:173], v240 offset:2048
	ds_read_b128 v[174:177], v240 offset:3072
	ds_read_b128 v[178:181], v240 offset:4096
	ds_read_b128 v[182:185], v240 offset:5120
	ds_read_b128 v[186:189], v240 offset:6144
	ds_read_b128 v[206:209], v240 offset:7168
	global_load_lds_dwordx4 v[210:211], off
	v_lshl_add_u64 v[210:211], s[56:57], 0, v[202:203]
	s_add_i32 m0, s53, 0xe000
	s_nop 0
	global_load_lds_dwordx4 v[210:211], off
	s_waitcnt vmcnt(8)
	s_waitcnt lgkmcnt(0)
	s_barrier
	s_setprio 1
	s_waitcnt lgkmcnt(0)
	v_mfma_f32_16x16x32_bf16 v[158:161], v[56:59], v[162:165], v[158:161]
	v_mfma_f32_16x16x32_bf16 v[154:157], v[66:69], v[162:165], v[154:157]
	v_mfma_f32_16x16x32_bf16 v[142:145], v[56:59], v[170:173], v[142:145]
	v_mfma_f32_16x16x32_bf16 v[138:141], v[66:69], v[170:173], v[138:141]
	v_mfma_f32_16x16x32_bf16 v[126:129], v[56:59], v[178:181], v[126:129]
	v_mfma_f32_16x16x32_bf16 v[122:125], v[66:69], v[178:181], v[122:125]
	v_mfma_f32_16x16x32_bf16 v[110:113], v[56:59], v[186:189], v[110:113]
	v_mfma_f32_16x16x32_bf16 v[106:109], v[66:69], v[186:189], v[106:109]
	v_mfma_f32_16x16x32_bf16 v[158:161], v[60:63], v[166:169], v[158:161]
	v_mfma_f32_16x16x32_bf16 v[154:157], v[70:73], v[166:169], v[154:157]
	v_mfma_f32_16x16x32_bf16 v[142:145], v[60:63], v[174:177], v[142:145]
	v_mfma_f32_16x16x32_bf16 v[138:141], v[70:73], v[174:177], v[138:141]
	v_mfma_f32_16x16x32_bf16 v[126:129], v[60:63], v[182:185], v[126:129]
	v_mfma_f32_16x16x32_bf16 v[122:125], v[70:73], v[182:185], v[122:125]
	v_mfma_f32_16x16x32_bf16 v[110:113], v[60:63], v[206:209], v[110:113]
	v_mfma_f32_16x16x32_bf16 v[106:109], v[70:73], v[206:209], v[106:109]
	v_mfma_f32_16x16x32_bf16 v[150:153], v[74:77], v[162:165], v[150:153]
	v_mfma_f32_16x16x32_bf16 v[146:149], v[82:85], v[162:165], v[146:149]
	v_mfma_f32_16x16x32_bf16 v[134:137], v[74:77], v[170:173], v[134:137]
	v_mfma_f32_16x16x32_bf16 v[130:133], v[82:85], v[170:173], v[130:133]
	v_mfma_f32_16x16x32_bf16 v[118:121], v[74:77], v[178:181], v[118:121]
	v_mfma_f32_16x16x32_bf16 v[114:117], v[82:85], v[178:181], v[114:117]
	v_mfma_f32_16x16x32_bf16 v[102:105], v[74:77], v[186:189], v[102:105]
	v_mfma_f32_16x16x32_bf16 v[98:101], v[82:85], v[186:189], v[98:101]
	v_mfma_f32_16x16x32_bf16 v[150:153], v[78:81], v[166:169], v[150:153]
	v_mfma_f32_16x16x32_bf16 v[146:149], v[86:89], v[166:169], v[146:149]
	v_mfma_f32_16x16x32_bf16 v[134:137], v[78:81], v[174:177], v[134:137]
	v_mfma_f32_16x16x32_bf16 v[130:133], v[86:89], v[174:177], v[130:133]
	v_mfma_f32_16x16x32_bf16 v[118:121], v[78:81], v[182:185], v[118:121]
	v_mfma_f32_16x16x32_bf16 v[114:117], v[86:89], v[182:185], v[114:117]
	v_mfma_f32_16x16x32_bf16 v[102:105], v[78:81], v[206:209], v[102:105]
	v_mfma_f32_16x16x32_bf16 v[98:101], v[86:89], v[206:209], v[98:101]
	s_setprio 0
	s_barrier
	s_add_i32 s0, s58, s45
	v_lshl_add_u64 v[210:211], s[34:35], 0, v[64:65]
	s_mov_b32 m0, s0
	ds_read_b128 v[162:165], v240 offset:16384
	ds_read_b128 v[166:169], v240 offset:17408
	ds_read_b128 v[170:173], v240 offset:18432
	ds_read_b128 v[174:177], v240 offset:19456
	ds_read_b128 v[178:181], v240 offset:20480
	ds_read_b128 v[182:185], v240 offset:21504
	ds_read_b128 v[186:189], v240 offset:22528
	ds_read_b128 v[206:209], v240 offset:23552
	global_load_lds_dwordx4 v[210:211], off
	s_add_i32 m0, s0, 0x2000
	s_add_u32 s0, s34, 0x40000
	v_lshl_add_u64 v[212:213], s[34:35], 0, v[196:197]
	s_addc_u32 s1, s35, 0
	s_add_i32 s58, s59, s45
	global_load_lds_dwordx4 v[212:213], off
	v_lshl_add_u64 v[214:215], s[0:1], 0, v[64:65]
	s_mov_b32 m0, s58
	v_lshl_add_u64 v[216:217], s[82:83], 0, v[198:199]
	global_load_lds_dwordx4 v[214:215], off
	v_lshl_add_u64 v[214:215], s[0:1], 0, v[196:197]
	s_add_i32 m0, s58, 0x2000
	s_nop 0
	global_load_lds_dwordx4 v[214:215], off
	v_lshl_add_u64 v[214:215], s[82:83], 0, v[200:201]
	s_mov_b32 m0, s53
	s_nop 0
	global_load_lds_dwordx4 v[214:215], off
	s_mov_b32 m0, s60
	s_nop 0
	global_load_lds_dwordx4 v[216:217], off
	s_waitcnt vmcnt(8)
	s_waitcnt lgkmcnt(0)
	s_barrier
	s_setprio 1
	s_waitcnt lgkmcnt(0)
	v_mfma_f32_16x16x32_bf16 v[94:97], v[56:59], v[162:165], v[94:97]
	v_mfma_f32_16x16x32_bf16 v[90:93], v[66:69], v[162:165], v[90:93]
	v_mfma_f32_16x16x32_bf16 v[44:47], v[56:59], v[170:173], v[44:47]
	v_mfma_f32_16x16x32_bf16 v[40:43], v[66:69], v[170:173], v[40:43]
	v_mfma_f32_16x16x32_bf16 v[28:31], v[56:59], v[178:181], v[28:31]
	v_mfma_f32_16x16x32_bf16 v[24:27], v[66:69], v[178:181], v[24:27]
	v_mfma_f32_16x16x32_bf16 v[12:15], v[56:59], v[186:189], v[12:15]
	v_mfma_f32_16x16x32_bf16 v[8:11], v[66:69], v[186:189], v[8:11]
	v_mfma_f32_16x16x32_bf16 v[94:97], v[60:63], v[166:169], v[94:97]
	v_mfma_f32_16x16x32_bf16 v[90:93], v[70:73], v[166:169], v[90:93]
	v_mfma_f32_16x16x32_bf16 v[44:47], v[60:63], v[174:177], v[44:47]
	v_mfma_f32_16x16x32_bf16 v[40:43], v[70:73], v[174:177], v[40:43]
	v_mfma_f32_16x16x32_bf16 v[28:31], v[60:63], v[182:185], v[28:31]
	v_mfma_f32_16x16x32_bf16 v[24:27], v[70:73], v[182:185], v[24:27]
	v_mfma_f32_16x16x32_bf16 v[12:15], v[60:63], v[206:209], v[12:15]
	v_mfma_f32_16x16x32_bf16 v[8:11], v[70:73], v[206:209], v[8:11]
	v_mfma_f32_16x16x32_bf16 v[52:55], v[74:77], v[162:165], v[52:55]
	v_mfma_f32_16x16x32_bf16 v[48:51], v[82:85], v[162:165], v[48:51]
	v_mfma_f32_16x16x32_bf16 v[36:39], v[74:77], v[170:173], v[36:39]
	v_mfma_f32_16x16x32_bf16 v[32:35], v[82:85], v[170:173], v[32:35]
	v_mfma_f32_16x16x32_bf16 v[20:23], v[74:77], v[178:181], v[20:23]
	v_mfma_f32_16x16x32_bf16 v[16:19], v[82:85], v[178:181], v[16:19]
	v_mfma_f32_16x16x32_bf16 v[4:7], v[74:77], v[186:189], v[4:7]
	v_mfma_f32_16x16x32_bf16 v[0:3], v[82:85], v[186:189], v[0:3]
	v_mfma_f32_16x16x32_bf16 v[52:55], v[78:81], v[166:169], v[52:55]
	v_mfma_f32_16x16x32_bf16 v[48:51], v[86:89], v[166:169], v[48:51]
	v_mfma_f32_16x16x32_bf16 v[36:39], v[78:81], v[174:177], v[36:39]
	v_mfma_f32_16x16x32_bf16 v[32:35], v[86:89], v[174:177], v[32:35]
	v_mfma_f32_16x16x32_bf16 v[20:23], v[78:81], v[182:185], v[20:23]
	v_mfma_f32_16x16x32_bf16 v[16:19], v[86:89], v[182:185], v[16:19]
	v_mfma_f32_16x16x32_bf16 v[4:7], v[78:81], v[206:209], v[4:7]
	v_mfma_f32_16x16x32_bf16 v[0:3], v[86:89], v[206:209], v[0:3]
	s_setprio 0
	s_barrier
	s_add_i32 s58, 0, 0x18000
	s_add_i32 s59, 0, 0x1c000
	v_add_u32_e32 v70, s58, v227
	v_add_u32_e32 v86, s59, v227
	ds_read_b128 v[56:59], v70
	ds_read_b128 v[60:63], v70 offset:1024
	ds_read_b128 v[66:69], v70 offset:2048
	ds_read_b128 v[70:73], v70 offset:3072
	ds_read_b128 v[74:77], v86
	ds_read_b128 v[78:81], v86 offset:1024
	ds_read_b128 v[82:85], v86 offset:2048
	ds_read_b128 v[86:89], v86 offset:3072
	s_add_u32 s0, s82, 0x40000
	s_addc_u32 s1, s83, 0
	s_mov_b32 m0, s61
	v_lshl_add_u64 v[218:219], s[0:1], 0, v[200:201]
	ds_read_b128 v[162:165], v240 offset:32768
	ds_read_b128 v[166:169], v240 offset:33792
	ds_read_b128 v[170:173], v240 offset:34816
	ds_read_b128 v[174:177], v240 offset:35840
	ds_read_b128 v[178:181], v240 offset:36864
	ds_read_b128 v[182:185], v240 offset:37888
	ds_read_b128 v[186:189], v240 offset:38912
	ds_read_b128 v[206:209], v240 offset:39936
	global_load_lds_dwordx4 v[218:219], off
	v_lshl_add_u64 v[218:219], s[0:1], 0, v[198:199]
	s_mov_b32 m0, s63
	s_nop 0
	global_load_lds_dwordx4 v[218:219], off
	s_waitcnt vmcnt(8)
	s_waitcnt lgkmcnt(0)
	s_barrier
	s_setprio 1
	s_waitcnt lgkmcnt(0)
	v_mfma_f32_16x16x32_bf16 v[158:161], v[56:59], v[162:165], v[158:161]
	v_mfma_f32_16x16x32_bf16 v[154:157], v[66:69], v[162:165], v[154:157]
	v_mfma_f32_16x16x32_bf16 v[142:145], v[56:59], v[170:173], v[142:145]
	v_mfma_f32_16x16x32_bf16 v[138:141], v[66:69], v[170:173], v[138:141]
	v_mfma_f32_16x16x32_bf16 v[126:129], v[56:59], v[178:181], v[126:129]
	v_mfma_f32_16x16x32_bf16 v[122:125], v[66:69], v[178:181], v[122:125]
	v_mfma_f32_16x16x32_bf16 v[110:113], v[56:59], v[186:189], v[110:113]
	v_mfma_f32_16x16x32_bf16 v[106:109], v[66:69], v[186:189], v[106:109]
	v_mfma_f32_16x16x32_bf16 v[158:161], v[60:63], v[166:169], v[158:161]
	v_mfma_f32_16x16x32_bf16 v[154:157], v[70:73], v[166:169], v[154:157]
	v_mfma_f32_16x16x32_bf16 v[142:145], v[60:63], v[174:177], v[142:145]
	v_mfma_f32_16x16x32_bf16 v[138:141], v[70:73], v[174:177], v[138:141]
	v_mfma_f32_16x16x32_bf16 v[126:129], v[60:63], v[182:185], v[126:129]
	v_mfma_f32_16x16x32_bf16 v[122:125], v[70:73], v[182:185], v[122:125]
	v_mfma_f32_16x16x32_bf16 v[110:113], v[60:63], v[206:209], v[110:113]
	v_mfma_f32_16x16x32_bf16 v[106:109], v[70:73], v[206:209], v[106:109]
	v_mfma_f32_16x16x32_bf16 v[150:153], v[74:77], v[162:165], v[150:153]
	v_mfma_f32_16x16x32_bf16 v[146:149], v[82:85], v[162:165], v[146:149]
	v_mfma_f32_16x16x32_bf16 v[134:137], v[74:77], v[170:173], v[134:137]
	v_mfma_f32_16x16x32_bf16 v[130:133], v[82:85], v[170:173], v[130:133]
	v_mfma_f32_16x16x32_bf16 v[118:121], v[74:77], v[178:181], v[118:121]
	v_mfma_f32_16x16x32_bf16 v[114:117], v[82:85], v[178:181], v[114:117]
	v_mfma_f32_16x16x32_bf16 v[102:105], v[74:77], v[186:189], v[102:105]
	v_mfma_f32_16x16x32_bf16 v[98:101], v[82:85], v[186:189], v[98:101]
	v_mfma_f32_16x16x32_bf16 v[150:153], v[78:81], v[166:169], v[150:153]
	v_mfma_f32_16x16x32_bf16 v[146:149], v[86:89], v[166:169], v[146:149]
	v_mfma_f32_16x16x32_bf16 v[134:137], v[78:81], v[174:177], v[134:137]
	v_mfma_f32_16x16x32_bf16 v[130:133], v[86:89], v[174:177], v[130:133]
	v_mfma_f32_16x16x32_bf16 v[118:121], v[78:81], v[182:185], v[118:121]
	v_mfma_f32_16x16x32_bf16 v[114:117], v[86:89], v[182:185], v[114:117]
	v_mfma_f32_16x16x32_bf16 v[102:105], v[78:81], v[206:209], v[102:105]
	v_mfma_f32_16x16x32_bf16 v[98:101], v[86:89], v[206:209], v[98:101]
	s_setprio 0
	s_barrier
	s_add_i32 s0, s58, s45
	v_lshl_add_u64 v[210:211], v[210:211], 0, s[30:31]
	s_mov_b32 m0, s0
	ds_read_b128 v[162:165], v240 offset:49152
	ds_read_b128 v[166:169], v240 offset:50176
	ds_read_b128 v[170:173], v240 offset:51200
	ds_read_b128 v[174:177], v240 offset:52224
	ds_read_b128 v[178:181], v240 offset:53248
	ds_read_b128 v[182:185], v240 offset:54272
	ds_read_b128 v[186:189], v240 offset:55296
	ds_read_b128 v[206:209], v240 offset:56320
	global_load_lds_dwordx4 v[210:211], off
	s_add_i32 m0, s0, 0x2000
	s_add_u32 s0, s34, 0x40080
	v_lshl_add_u64 v[210:211], v[212:213], 0, s[30:31]
	s_addc_u32 s1, s35, 0
	s_add_i32 s34, s59, s45
	global_load_lds_dwordx4 v[210:211], off
	v_lshl_add_u64 v[210:211], s[0:1], 0, v[64:65]
	s_mov_b32 m0, s34
	s_nop 0
	global_load_lds_dwordx4 v[210:211], off
	v_lshl_add_u64 v[210:211], s[0:1], 0, v[196:197]
	s_add_i32 m0, s34, 0x2000
	s_nop 0
	global_load_lds_dwordx4 v[210:211], off
	v_lshl_add_u64 v[210:211], v[214:215], 0, s[30:31]
	s_mov_b32 m0, s88
	s_nop 0
	global_load_lds_dwordx4 v[210:211], off
	v_lshl_add_u64 v[210:211], v[216:217], 0, s[30:31]
	s_mov_b32 m0, s89
	s_nop 0
	global_load_lds_dwordx4 v[210:211], off
	s_waitcnt vmcnt(8)
	s_waitcnt lgkmcnt(0)
	s_barrier
	s_setprio 1
	s_waitcnt lgkmcnt(0)
	v_mfma_f32_16x16x32_bf16 v[94:97], v[56:59], v[162:165], v[94:97]
	v_mfma_f32_16x16x32_bf16 v[90:93], v[66:69], v[162:165], v[90:93]
	v_mfma_f32_16x16x32_bf16 v[44:47], v[56:59], v[170:173], v[44:47]
	v_mfma_f32_16x16x32_bf16 v[40:43], v[66:69], v[170:173], v[40:43]
	v_mfma_f32_16x16x32_bf16 v[28:31], v[56:59], v[178:181], v[28:31]
	v_mfma_f32_16x16x32_bf16 v[24:27], v[66:69], v[178:181], v[24:27]
	v_mfma_f32_16x16x32_bf16 v[12:15], v[56:59], v[186:189], v[12:15]
	v_mfma_f32_16x16x32_bf16 v[8:11], v[66:69], v[186:189], v[8:11]
	v_mfma_f32_16x16x32_bf16 v[94:97], v[60:63], v[166:169], v[94:97]
	v_mfma_f32_16x16x32_bf16 v[90:93], v[70:73], v[166:169], v[90:93]
	v_mfma_f32_16x16x32_bf16 v[44:47], v[60:63], v[174:177], v[44:47]
	v_mfma_f32_16x16x32_bf16 v[40:43], v[70:73], v[174:177], v[40:43]
	v_mfma_f32_16x16x32_bf16 v[28:31], v[60:63], v[182:185], v[28:31]
	v_mfma_f32_16x16x32_bf16 v[24:27], v[70:73], v[182:185], v[24:27]
	v_mfma_f32_16x16x32_bf16 v[12:15], v[60:63], v[206:209], v[12:15]
	v_mfma_f32_16x16x32_bf16 v[8:11], v[70:73], v[206:209], v[8:11]
	v_mfma_f32_16x16x32_bf16 v[52:55], v[74:77], v[162:165], v[52:55]
	v_mfma_f32_16x16x32_bf16 v[48:51], v[82:85], v[162:165], v[48:51]
	v_mfma_f32_16x16x32_bf16 v[36:39], v[74:77], v[170:173], v[36:39]
	v_mfma_f32_16x16x32_bf16 v[32:35], v[82:85], v[170:173], v[32:35]
	v_mfma_f32_16x16x32_bf16 v[20:23], v[74:77], v[178:181], v[20:23]
	v_mfma_f32_16x16x32_bf16 v[16:19], v[82:85], v[178:181], v[16:19]
	v_mfma_f32_16x16x32_bf16 v[4:7], v[74:77], v[186:189], v[4:7]
	v_mfma_f32_16x16x32_bf16 v[0:3], v[82:85], v[186:189], v[0:3]
	v_mfma_f32_16x16x32_bf16 v[52:55], v[78:81], v[166:169], v[52:55]
	v_mfma_f32_16x16x32_bf16 v[48:51], v[86:89], v[166:169], v[48:51]
	v_mfma_f32_16x16x32_bf16 v[36:39], v[78:81], v[174:177], v[36:39]
	v_mfma_f32_16x16x32_bf16 v[32:35], v[86:89], v[174:177], v[32:35]
	v_mfma_f32_16x16x32_bf16 v[20:23], v[78:81], v[182:185], v[20:23]
	v_mfma_f32_16x16x32_bf16 v[16:19], v[86:89], v[182:185], v[16:19]
	v_mfma_f32_16x16x32_bf16 v[4:7], v[78:81], v[206:209], v[4:7]
	v_mfma_f32_16x16x32_bf16 v[0:3], v[86:89], v[206:209], v[0:3]
	s_setprio 0
	s_barrier
	s_add_i32 vcc_lo, vcc_lo, 2
	s_add_u32 s67, s67, 0x100
	s_addc_u32 s96, s96, 0
	s_add_u32 s56, s56, 0x100
	s_addc_u32 s57, s57, 0
	s_cmp_gt_u32 vcc_lo, 13
	s_cbranch_scc0 .LBB0_1884
	s_and_b64 vcc, exec, s[20:21]
	s_cbranch_vccz .LBB0_1887
	s_barrier

.LBB0_2125:
	s_add_u32 s0, s56, 0xfffc0080
	s_addc_u32 s1, s57, -1
	s_add_i32 s58, 0, 0x10000
	s_cmp_eq_u32 vcc_lo, 12
	s_cselect_b32 s77, s13, s1
	s_cselect_b32 s76, s66, s0
	s_cselect_b32 s35, s67, s96
	s_cselect_b32 s34, s81, s83
	s_add_i32 s59, 0, 0x14000
	v_add_u32_e32 v44, s58, v162
	v_add_u32_e32 v172, s59, v162
	ds_read_b128 v[32:35], v44
	ds_read_b128 v[36:39], v44 offset:1024
	ds_read_b128 v[40:43], v44 offset:2048
	ds_read_b128 v[44:47], v44 offset:3072
	ds_read_b128 v[156:159], v172
	ds_read_b128 v[164:167], v172 offset:1024
	ds_read_b128 v[168:171], v172 offset:2048
	ds_read_b128 v[172:175], v172 offset:3072
	v_lshl_add_u64 v[188:189], s[56:57], 0, v[154:155]
	s_add_i32 m0, s61, 0xc000
	ds_read_b128 v[176:179], v163
	ds_read_b128 v[180:183], v163 offset:1024
	ds_read_b128 v[184:187], v163 offset:2048
	ds_read_b128 v[196:199], v163 offset:3072
	ds_read_b128 v[200:203], v163 offset:4096
	ds_read_b128 v[204:207], v163 offset:5120
	ds_read_b128 v[208:211], v163 offset:6144
	ds_read_b128 v[212:215], v163 offset:7168
	global_load_lds_dwordx4 v[188:189], off
	v_lshl_add_u64 v[188:189], s[56:57], 0, v[152:153]
	s_add_i32 m0, s61, 0xe000
	s_nop 0
	global_load_lds_dwordx4 v[188:189], off
	s_waitcnt vmcnt(8)
	s_waitcnt lgkmcnt(0)
	s_barrier
	s_setprio 1
	s_waitcnt lgkmcnt(0)
	v_mfma_f32_16x16x32_bf16 v[142:145], v[32:35], v[176:179], v[142:145]
	v_mfma_f32_16x16x32_bf16 v[138:141], v[40:43], v[176:179], v[138:141]
	v_mfma_f32_16x16x32_bf16 v[126:129], v[32:35], v[184:187], v[126:129]
	v_mfma_f32_16x16x32_bf16 v[122:125], v[40:43], v[184:187], v[122:125]
	v_mfma_f32_16x16x32_bf16 v[110:113], v[32:35], v[200:203], v[110:113]
	v_mfma_f32_16x16x32_bf16 v[106:109], v[40:43], v[200:203], v[106:109]
	v_mfma_f32_16x16x32_bf16 v[94:97], v[32:35], v[208:211], v[94:97]
	v_mfma_f32_16x16x32_bf16 v[90:93], v[40:43], v[208:211], v[90:93]
	v_mfma_f32_16x16x32_bf16 v[142:145], v[36:39], v[180:183], v[142:145]
	v_mfma_f32_16x16x32_bf16 v[138:141], v[44:47], v[180:183], v[138:141]
	v_mfma_f32_16x16x32_bf16 v[126:129], v[36:39], v[196:199], v[126:129]
	v_mfma_f32_16x16x32_bf16 v[122:125], v[44:47], v[196:199], v[122:125]
	v_mfma_f32_16x16x32_bf16 v[110:113], v[36:39], v[204:207], v[110:113]
	v_mfma_f32_16x16x32_bf16 v[106:109], v[44:47], v[204:207], v[106:109]
	v_mfma_f32_16x16x32_bf16 v[94:97], v[36:39], v[212:215], v[94:97]
	v_mfma_f32_16x16x32_bf16 v[90:93], v[44:47], v[212:215], v[90:93]
	v_mfma_f32_16x16x32_bf16 v[134:137], v[156:159], v[176:179], v[134:137]
	v_mfma_f32_16x16x32_bf16 v[130:133], v[168:171], v[176:179], v[130:133]
	v_mfma_f32_16x16x32_bf16 v[118:121], v[156:159], v[184:187], v[118:121]
	v_mfma_f32_16x16x32_bf16 v[114:117], v[168:171], v[184:187], v[114:117]
	v_mfma_f32_16x16x32_bf16 v[102:105], v[156:159], v[200:203], v[102:105]
	v_mfma_f32_16x16x32_bf16 v[98:101], v[168:171], v[200:203], v[98:101]
	v_mfma_f32_16x16x32_bf16 v[86:89], v[156:159], v[208:211], v[86:89]
	v_mfma_f32_16x16x32_bf16 v[82:85], v[168:171], v[208:211], v[82:85]
	v_mfma_f32_16x16x32_bf16 v[134:137], v[164:167], v[180:183], v[134:137]
	v_mfma_f32_16x16x32_bf16 v[130:133], v[172:175], v[180:183], v[130:133]
	v_mfma_f32_16x16x32_bf16 v[118:121], v[164:167], v[196:199], v[118:121]
	v_mfma_f32_16x16x32_bf16 v[114:117], v[172:175], v[196:199], v[114:117]
	v_mfma_f32_16x16x32_bf16 v[102:105], v[164:167], v[204:207], v[102:105]
	v_mfma_f32_16x16x32_bf16 v[98:101], v[172:175], v[204:207], v[98:101]
	v_mfma_f32_16x16x32_bf16 v[86:89], v[164:167], v[212:215], v[86:89]
	v_mfma_f32_16x16x32_bf16 v[82:85], v[172:175], v[212:215], v[82:85]
	s_setprio 0
	s_barrier
	s_add_i32 s0, s58, s60
	v_lshl_add_u64 v[188:189], s[34:35], 0, v[64:65]
	s_mov_b32 m0, s0
	ds_read_b128 v[176:179], v163 offset:16384
	ds_read_b128 v[180:183], v163 offset:17408
	ds_read_b128 v[184:187], v163 offset:18432
	ds_read_b128 v[196:199], v163 offset:19456
	ds_read_b128 v[200:203], v163 offset:20480
	ds_read_b128 v[204:207], v163 offset:21504
	ds_read_b128 v[208:211], v163 offset:22528
	ds_read_b128 v[212:215], v163 offset:23552
	global_load_lds_dwordx4 v[188:189], off
	s_add_i32 m0, s0, 0x2000
	s_add_u32 s0, s34, 0x40000
	v_lshl_add_u64 v[216:217], s[34:35], 0, v[146:147]
	s_addc_u32 s1, s35, 0
	s_add_i32 s58, s59, s60
	global_load_lds_dwordx4 v[216:217], off
	v_lshl_add_u64 v[218:219], s[0:1], 0, v[64:65]
	s_mov_b32 m0, s58
	v_lshl_add_u64 v[220:221], s[76:77], 0, v[148:149]
	global_load_lds_dwordx4 v[218:219], off
	v_lshl_add_u64 v[218:219], s[0:1], 0, v[146:147]
	s_add_i32 m0, s58, 0x2000
	s_nop 0
	global_load_lds_dwordx4 v[218:219], off
	v_lshl_add_u64 v[218:219], s[76:77], 0, v[150:151]
	s_mov_b32 m0, s61
	s_nop 0
	global_load_lds_dwordx4 v[218:219], off
	s_mov_b32 m0, s63
	s_nop 0
	global_load_lds_dwordx4 v[220:221], off
	s_waitcnt vmcnt(8)
	s_waitcnt lgkmcnt(0)
	s_barrier
	s_setprio 1
	s_waitcnt lgkmcnt(0)
	v_mfma_f32_16x16x32_bf16 v[78:81], v[32:35], v[176:179], v[78:81]
	v_mfma_f32_16x16x32_bf16 v[74:77], v[40:43], v[176:179], v[74:77]
	v_mfma_f32_16x16x32_bf16 v[60:63], v[32:35], v[184:187], v[60:63]
	v_mfma_f32_16x16x32_bf16 v[56:59], v[40:43], v[184:187], v[56:59]
	v_mfma_f32_16x16x32_bf16 v[28:31], v[32:35], v[200:203], v[28:31]
	v_mfma_f32_16x16x32_bf16 v[24:27], v[40:43], v[200:203], v[24:27]
	v_mfma_f32_16x16x32_bf16 v[12:15], v[32:35], v[208:211], v[12:15]
	v_mfma_f32_16x16x32_bf16 v[8:11], v[40:43], v[208:211], v[8:11]
	v_mfma_f32_16x16x32_bf16 v[78:81], v[36:39], v[180:183], v[78:81]
	v_mfma_f32_16x16x32_bf16 v[74:77], v[44:47], v[180:183], v[74:77]
	v_mfma_f32_16x16x32_bf16 v[60:63], v[36:39], v[196:199], v[60:63]
	v_mfma_f32_16x16x32_bf16 v[56:59], v[44:47], v[196:199], v[56:59]
	v_mfma_f32_16x16x32_bf16 v[28:31], v[36:39], v[204:207], v[28:31]
	v_mfma_f32_16x16x32_bf16 v[24:27], v[44:47], v[204:207], v[24:27]
	v_mfma_f32_16x16x32_bf16 v[12:15], v[36:39], v[212:215], v[12:15]
	v_mfma_f32_16x16x32_bf16 v[8:11], v[44:47], v[212:215], v[8:11]
	v_mfma_f32_16x16x32_bf16 v[20:23], v[156:159], v[200:203], v[20:23]
	v_mfma_f32_16x16x32_bf16 v[16:19], v[168:171], v[200:203], v[16:19]
	v_mfma_f32_16x16x32_bf16 v[4:7], v[156:159], v[208:211], v[4:7]
	v_mfma_f32_16x16x32_bf16 v[0:3], v[168:171], v[208:211], v[0:3]
	v_mfma_f32_16x16x32_bf16 v[32:35], v[156:159], v[176:179], v[70:73]
	v_mfma_f32_16x16x32_bf16 v[36:39], v[168:171], v[176:179], v[66:69]
	v_mfma_f32_16x16x32_bf16 v[40:43], v[156:159], v[184:187], v[52:55]
	v_mfma_f32_16x16x32_bf16 v[44:47], v[168:171], v[184:187], v[48:51]
	v_mfma_f32_16x16x32_bf16 v[20:23], v[164:167], v[204:207], v[20:23]
	v_mfma_f32_16x16x32_bf16 v[16:19], v[172:175], v[204:207], v[16:19]
	v_mfma_f32_16x16x32_bf16 v[4:7], v[164:167], v[212:215], v[4:7]
	v_mfma_f32_16x16x32_bf16 v[0:3], v[172:175], v[212:215], v[0:3]
	v_mfma_f32_16x16x32_bf16 v[32:35], v[164:167], v[180:183], v[32:35]
	v_mfma_f32_16x16x32_bf16 v[36:39], v[172:175], v[180:183], v[36:39]
	v_mfma_f32_16x16x32_bf16 v[40:43], v[164:167], v[196:199], v[40:43]
	v_mfma_f32_16x16x32_bf16 v[44:47], v[172:175], v[196:199], v[44:47]
	s_setprio 0
	s_barrier
	s_add_i32 s58, 0, 0x18000
	s_add_i32 s59, 0, 0x1c000
	v_add_u32_e32 v70, s58, v162
	v_add_u32_e32 v172, s59, v162
	ds_read_b128 v[48:51], v70
	ds_read_b128 v[52:55], v70 offset:1024
	ds_read_b128 v[66:69], v70 offset:2048
	ds_read_b128 v[70:73], v70 offset:3072
	ds_read_b128 v[156:159], v172
	ds_read_b128 v[164:167], v172 offset:1024
	ds_read_b128 v[168:171], v172 offset:2048
	ds_read_b128 v[172:175], v172 offset:3072
	s_add_u32 s0, s76, 0x40000
	s_addc_u32 s1, s77, 0
	s_mov_b32 m0, s75
	v_lshl_add_u64 v[222:223], s[0:1], 0, v[150:151]
	ds_read_b128 v[176:179], v163 offset:32768
	ds_read_b128 v[180:183], v163 offset:33792
	ds_read_b128 v[184:187], v163 offset:34816
	ds_read_b128 v[196:199], v163 offset:35840
	ds_read_b128 v[200:203], v163 offset:36864
	ds_read_b128 v[204:207], v163 offset:37888
	ds_read_b128 v[208:211], v163 offset:38912
	ds_read_b128 v[212:215], v163 offset:39936
	global_load_lds_dwordx4 v[222:223], off
	v_lshl_add_u64 v[222:223], s[0:1], 0, v[148:149]
	s_mov_b32 m0, s79
	s_nop 0
	global_load_lds_dwordx4 v[222:223], off
	s_waitcnt vmcnt(8)
	s_waitcnt lgkmcnt(0)
	s_barrier
	s_setprio 1
	s_waitcnt lgkmcnt(0)
	v_mfma_f32_16x16x32_bf16 v[142:145], v[48:51], v[176:179], v[142:145]
	v_mfma_f32_16x16x32_bf16 v[138:141], v[66:69], v[176:179], v[138:141]
	v_mfma_f32_16x16x32_bf16 v[126:129], v[48:51], v[184:187], v[126:129]
	v_mfma_f32_16x16x32_bf16 v[122:125], v[66:69], v[184:187], v[122:125]
	v_mfma_f32_16x16x32_bf16 v[110:113], v[48:51], v[200:203], v[110:113]
	v_mfma_f32_16x16x32_bf16 v[106:109], v[66:69], v[200:203], v[106:109]
	v_mfma_f32_16x16x32_bf16 v[94:97], v[48:51], v[208:211], v[94:97]
	v_mfma_f32_16x16x32_bf16 v[90:93], v[66:69], v[208:211], v[90:93]
	v_mfma_f32_16x16x32_bf16 v[142:145], v[52:55], v[180:183], v[142:145]
	v_mfma_f32_16x16x32_bf16 v[138:141], v[70:73], v[180:183], v[138:141]
	v_mfma_f32_16x16x32_bf16 v[126:129], v[52:55], v[196:199], v[126:129]
	v_mfma_f32_16x16x32_bf16 v[122:125], v[70:73], v[196:199], v[122:125]
	v_mfma_f32_16x16x32_bf16 v[110:113], v[52:55], v[204:207], v[110:113]
	v_mfma_f32_16x16x32_bf16 v[106:109], v[70:73], v[204:207], v[106:109]
	v_mfma_f32_16x16x32_bf16 v[94:97], v[52:55], v[212:215], v[94:97]
	v_mfma_f32_16x16x32_bf16 v[90:93], v[70:73], v[212:215], v[90:93]
	v_mfma_f32_16x16x32_bf16 v[134:137], v[156:159], v[176:179], v[134:137]
	v_mfma_f32_16x16x32_bf16 v[130:133], v[168:171], v[176:179], v[130:133]
	v_mfma_f32_16x16x32_bf16 v[118:121], v[156:159], v[184:187], v[118:121]
	v_mfma_f32_16x16x32_bf16 v[114:117], v[168:171], v[184:187], v[114:117]
	v_mfma_f32_16x16x32_bf16 v[102:105], v[156:159], v[200:203], v[102:105]
	v_mfma_f32_16x16x32_bf16 v[98:101], v[168:171], v[200:203], v[98:101]
	v_mfma_f32_16x16x32_bf16 v[86:89], v[156:159], v[208:211], v[86:89]
	v_mfma_f32_16x16x32_bf16 v[82:85], v[168:171], v[208:211], v[82:85]
	v_mfma_f32_16x16x32_bf16 v[134:137], v[164:167], v[180:183], v[134:137]
	v_mfma_f32_16x16x32_bf16 v[130:133], v[172:175], v[180:183], v[130:133]
	v_mfma_f32_16x16x32_bf16 v[118:121], v[164:167], v[196:199], v[118:121]
	v_mfma_f32_16x16x32_bf16 v[114:117], v[172:175], v[196:199], v[114:117]
	v_mfma_f32_16x16x32_bf16 v[102:105], v[164:167], v[204:207], v[102:105]
	v_mfma_f32_16x16x32_bf16 v[98:101], v[172:175], v[204:207], v[98:101]
	v_mfma_f32_16x16x32_bf16 v[86:89], v[164:167], v[212:215], v[86:89]
	v_mfma_f32_16x16x32_bf16 v[82:85], v[172:175], v[212:215], v[82:85]
	s_setprio 0
	s_barrier
	s_add_i32 s0, s58, s60
	v_lshl_add_u64 v[188:189], v[188:189], 0, s[30:31]
	s_mov_b32 m0, s0
	ds_read_b128 v[176:179], v163 offset:49152
	ds_read_b128 v[180:183], v163 offset:50176
	ds_read_b128 v[184:187], v163 offset:51200
	ds_read_b128 v[196:199], v163 offset:52224
	ds_read_b128 v[200:203], v163 offset:53248
	ds_read_b128 v[204:207], v163 offset:54272
	ds_read_b128 v[208:211], v163 offset:55296
	ds_read_b128 v[212:215], v163 offset:56320
	global_load_lds_dwordx4 v[188:189], off
	s_add_i32 m0, s0, 0x2000
	s_add_u32 s0, s34, 0x40080
	v_lshl_add_u64 v[188:189], v[216:217], 0, s[30:31]
	s_addc_u32 s1, s35, 0
	s_add_i32 s34, s59, s60
	global_load_lds_dwordx4 v[188:189], off
	v_lshl_add_u64 v[188:189], s[0:1], 0, v[64:65]
	s_mov_b32 m0, s34
	s_nop 0
	global_load_lds_dwordx4 v[188:189], off
	v_lshl_add_u64 v[188:189], s[0:1], 0, v[146:147]
	s_add_i32 m0, s34, 0x2000
	s_nop 0
	global_load_lds_dwordx4 v[188:189], off
	v_lshl_add_u64 v[188:189], v[218:219], 0, s[30:31]
	s_mov_b32 m0, s4
	s_nop 0
	global_load_lds_dwordx4 v[188:189], off
	v_lshl_add_u64 v[188:189], v[220:221], 0, s[30:31]
	s_mov_b32 m0, s5
	s_nop 0
	global_load_lds_dwordx4 v[188:189], off
	s_waitcnt vmcnt(8)
	s_waitcnt lgkmcnt(0)
	s_barrier
	s_setprio 1
	s_waitcnt lgkmcnt(0)
	v_mfma_f32_16x16x32_bf16 v[78:81], v[48:51], v[176:179], v[78:81]
	v_mfma_f32_16x16x32_bf16 v[74:77], v[66:69], v[176:179], v[74:77]
	v_mfma_f32_16x16x32_bf16 v[60:63], v[48:51], v[184:187], v[60:63]
	v_mfma_f32_16x16x32_bf16 v[56:59], v[66:69], v[184:187], v[56:59]
	v_mfma_f32_16x16x32_bf16 v[28:31], v[48:51], v[200:203], v[28:31]
	v_mfma_f32_16x16x32_bf16 v[24:27], v[66:69], v[200:203], v[24:27]
	v_mfma_f32_16x16x32_bf16 v[12:15], v[48:51], v[208:211], v[12:15]
	v_mfma_f32_16x16x32_bf16 v[8:11], v[66:69], v[208:211], v[8:11]
	v_mfma_f32_16x16x32_bf16 v[78:81], v[52:55], v[180:183], v[78:81]
	v_mfma_f32_16x16x32_bf16 v[74:77], v[70:73], v[180:183], v[74:77]
	v_mfma_f32_16x16x32_bf16 v[60:63], v[52:55], v[196:199], v[60:63]
	v_mfma_f32_16x16x32_bf16 v[56:59], v[70:73], v[196:199], v[56:59]
	v_mfma_f32_16x16x32_bf16 v[28:31], v[52:55], v[204:207], v[28:31]
	v_mfma_f32_16x16x32_bf16 v[24:27], v[70:73], v[204:207], v[24:27]
	v_mfma_f32_16x16x32_bf16 v[12:15], v[52:55], v[212:215], v[12:15]
	v_mfma_f32_16x16x32_bf16 v[8:11], v[70:73], v[212:215], v[8:11]
	v_mfma_f32_16x16x32_bf16 v[32:35], v[156:159], v[176:179], v[32:35]
	v_mfma_f32_16x16x32_bf16 v[70:73], v[164:167], v[180:183], v[32:35]
	v_mfma_f32_16x16x32_bf16 v[32:35], v[168:171], v[176:179], v[36:39]
	v_mfma_f32_16x16x32_bf16 v[66:69], v[172:175], v[180:183], v[32:35]
	v_mfma_f32_16x16x32_bf16 v[32:35], v[156:159], v[184:187], v[40:43]
	v_mfma_f32_16x16x32_bf16 v[52:55], v[164:167], v[196:199], v[32:35]
	v_mfma_f32_16x16x32_bf16 v[32:35], v[168:171], v[184:187], v[44:47]
	v_mfma_f32_16x16x32_bf16 v[20:23], v[156:159], v[200:203], v[20:23]
	v_mfma_f32_16x16x32_bf16 v[16:19], v[168:171], v[200:203], v[16:19]
	v_mfma_f32_16x16x32_bf16 v[4:7], v[156:159], v[208:211], v[4:7]
	v_mfma_f32_16x16x32_bf16 v[0:3], v[168:171], v[208:211], v[0:3]
	v_mfma_f32_16x16x32_bf16 v[48:51], v[172:175], v[196:199], v[32:35]
	v_mfma_f32_16x16x32_bf16 v[20:23], v[164:167], v[204:207], v[20:23]
	v_mfma_f32_16x16x32_bf16 v[16:19], v[172:175], v[204:207], v[16:19]
	v_mfma_f32_16x16x32_bf16 v[4:7], v[164:167], v[212:215], v[4:7]
	v_mfma_f32_16x16x32_bf16 v[0:3], v[172:175], v[212:215], v[0:3]
	s_setprio 0
	s_barrier
	s_add_i32 vcc_lo, vcc_lo, 2
	s_add_u32 s83, s83, 0x100
	s_addc_u32 s96, s96, 0
	s_add_u32 s56, s56, 0x100
	s_addc_u32 s57, s57, 0
	s_cmp_gt_u32 vcc_lo, 13
	s_cbranch_scc0 .LBB0_2125
	s_and_b64 vcc, exec, s[24:25]
	s_cbranch_vccz .LBB0_2128
	s_barrier

.LBB0_2178:
	s_add_u32 s8, s6, 0xfff00080
	s_addc_u32 s9, s7, -1
	s_add_i32 s58, 0, 0x10000
	s_cmp_eq_u32 vcc_hi, 60
	s_cselect_b32 s35, s57, s9
	s_cselect_b32 s34, s90, s8
	s_cselect_b32 s9, s25, vcc_lo
	s_cselect_b32 s8, s91, s96
	s_add_i32 s70, 0, 0x14000
	v_add_u32_e32 v78, s58, v241
	v_add_u32_e32 v102, s70, v241
	ds_read_b128 v[66:69], v78
	ds_read_b128 v[70:73], v78 offset:1024
	ds_read_b128 v[74:77], v78 offset:2048
	ds_read_b128 v[78:81], v78 offset:3072
	ds_read_b128 v[82:85], v102
	ds_read_b128 v[90:93], v102 offset:1024
	ds_read_b128 v[98:101], v102 offset:2048
	ds_read_b128 v[102:105], v102 offset:3072
	v_lshl_add_u64 v[210:211], s[6:7], 0, v[204:205]
	s_add_i32 m0, s61, 0xc000
	ds_read_b128 v[162:165], v242
	ds_read_b128 v[166:169], v242 offset:1024
	ds_read_b128 v[170:173], v242 offset:2048
	ds_read_b128 v[174:177], v242 offset:3072
	ds_read_b128 v[178:181], v242 offset:4096
	ds_read_b128 v[182:185], v242 offset:5120
	ds_read_b128 v[186:189], v242 offset:6144
	ds_read_b128 v[206:209], v242 offset:7168
	global_load_lds_dwordx4 v[210:211], off
	v_lshl_add_u64 v[210:211], s[6:7], 0, v[202:203]
	s_add_i32 m0, s61, 0xe000
	s_nop 0
	global_load_lds_dwordx4 v[210:211], off
	s_waitcnt vmcnt(8)
	s_waitcnt lgkmcnt(0)
	s_barrier
	s_setprio 1
	s_waitcnt lgkmcnt(0)
	v_mfma_f32_16x16x32_bf16 v[158:161], v[66:69], v[162:165], v[158:161]
	v_mfma_f32_16x16x32_bf16 v[154:157], v[74:77], v[162:165], v[154:157]
	v_mfma_f32_16x16x32_bf16 v[142:145], v[66:69], v[170:173], v[142:145]
	v_mfma_f32_16x16x32_bf16 v[138:141], v[74:77], v[170:173], v[138:141]
	v_mfma_f32_16x16x32_bf16 v[126:129], v[66:69], v[178:181], v[126:129]
	v_mfma_f32_16x16x32_bf16 v[122:125], v[74:77], v[178:181], v[122:125]
	v_mfma_f32_16x16x32_bf16 v[110:113], v[66:69], v[186:189], v[110:113]
	v_mfma_f32_16x16x32_bf16 v[106:109], v[74:77], v[186:189], v[106:109]
	v_mfma_f32_16x16x32_bf16 v[158:161], v[70:73], v[166:169], v[158:161]
	v_mfma_f32_16x16x32_bf16 v[154:157], v[78:81], v[166:169], v[154:157]
	v_mfma_f32_16x16x32_bf16 v[142:145], v[70:73], v[174:177], v[142:145]
	v_mfma_f32_16x16x32_bf16 v[138:141], v[78:81], v[174:177], v[138:141]
	v_mfma_f32_16x16x32_bf16 v[126:129], v[70:73], v[182:185], v[126:129]
	v_mfma_f32_16x16x32_bf16 v[122:125], v[78:81], v[182:185], v[122:125]
	v_mfma_f32_16x16x32_bf16 v[110:113], v[70:73], v[206:209], v[110:113]
	v_mfma_f32_16x16x32_bf16 v[106:109], v[78:81], v[206:209], v[106:109]
	v_mfma_f32_16x16x32_bf16 v[150:153], v[82:85], v[162:165], v[150:153]
	v_mfma_f32_16x16x32_bf16 v[146:149], v[98:101], v[162:165], v[146:149]
	v_mfma_f32_16x16x32_bf16 v[134:137], v[82:85], v[170:173], v[134:137]
	v_mfma_f32_16x16x32_bf16 v[130:133], v[98:101], v[170:173], v[130:133]
	v_mfma_f32_16x16x32_bf16 v[118:121], v[82:85], v[178:181], v[118:121]
	v_mfma_f32_16x16x32_bf16 v[114:117], v[98:101], v[178:181], v[114:117]
	v_mfma_f32_16x16x32_bf16 v[94:97], v[82:85], v[186:189], v[94:97]
	v_mfma_f32_16x16x32_bf16 v[86:89], v[98:101], v[186:189], v[86:89]
	v_mfma_f32_16x16x32_bf16 v[150:153], v[90:93], v[166:169], v[150:153]
	v_mfma_f32_16x16x32_bf16 v[146:149], v[102:105], v[166:169], v[146:149]
	v_mfma_f32_16x16x32_bf16 v[134:137], v[90:93], v[174:177], v[134:137]
	v_mfma_f32_16x16x32_bf16 v[130:133], v[102:105], v[174:177], v[130:133]
	v_mfma_f32_16x16x32_bf16 v[118:121], v[90:93], v[182:185], v[118:121]
	v_mfma_f32_16x16x32_bf16 v[114:117], v[102:105], v[182:185], v[114:117]
	v_mfma_f32_16x16x32_bf16 v[94:97], v[90:93], v[206:209], v[94:97]
	v_mfma_f32_16x16x32_bf16 v[86:89], v[102:105], v[206:209], v[86:89]
	s_setprio 0
	s_barrier
	s_add_i32 s58, s58, s60
	v_lshl_add_u64 v[210:211], s[8:9], 0, v[64:65]
	s_mov_b32 m0, s58
	ds_read_b128 v[162:165], v242 offset:16384
	ds_read_b128 v[166:169], v242 offset:17408
	ds_read_b128 v[170:173], v242 offset:18432
	ds_read_b128 v[174:177], v242 offset:19456
	ds_read_b128 v[178:181], v242 offset:20480
	ds_read_b128 v[182:185], v242 offset:21504
	ds_read_b128 v[186:189], v242 offset:22528
	ds_read_b128 v[206:209], v242 offset:23552
	global_load_lds_dwordx4 v[210:211], off
	s_add_i32 m0, s58, 0x2000
	s_add_u32 s58, s8, 0x100000
	v_lshl_add_u64 v[212:213], s[8:9], 0, v[196:197]
	s_addc_u32 s59, s9, 0
	s_add_i32 s70, s70, s60
	global_load_lds_dwordx4 v[212:213], off
	v_lshl_add_u64 v[214:215], s[58:59], 0, v[64:65]
	s_mov_b32 m0, s70
	v_lshl_add_u64 v[216:217], s[34:35], 0, v[198:199]
	global_load_lds_dwordx4 v[214:215], off
	v_lshl_add_u64 v[214:215], s[58:59], 0, v[196:197]
	s_add_i32 m0, s70, 0x2000
	s_nop 0
	global_load_lds_dwordx4 v[214:215], off
	v_lshl_add_u64 v[214:215], s[34:35], 0, v[200:201]
	s_mov_b32 m0, s61
	s_nop 0
	global_load_lds_dwordx4 v[214:215], off
	s_mov_b32 m0, s63
	s_nop 0
	global_load_lds_dwordx4 v[216:217], off
	s_waitcnt vmcnt(8)
	s_waitcnt lgkmcnt(0)
	s_barrier
	s_setprio 1
	s_waitcnt lgkmcnt(0)
	v_mfma_f32_16x16x32_bf16 v[60:63], v[66:69], v[162:165], v[60:63]
	v_mfma_f32_16x16x32_bf16 v[56:59], v[74:77], v[162:165], v[56:59]
	v_mfma_f32_16x16x32_bf16 v[44:47], v[66:69], v[170:173], v[44:47]
	v_mfma_f32_16x16x32_bf16 v[40:43], v[74:77], v[170:173], v[40:43]
	v_mfma_f32_16x16x32_bf16 v[28:31], v[66:69], v[178:181], v[28:31]
	v_mfma_f32_16x16x32_bf16 v[24:27], v[74:77], v[178:181], v[24:27]
	v_mfma_f32_16x16x32_bf16 v[12:15], v[66:69], v[186:189], v[12:15]
	v_mfma_f32_16x16x32_bf16 v[8:11], v[74:77], v[186:189], v[8:11]
	v_mfma_f32_16x16x32_bf16 v[60:63], v[70:73], v[166:169], v[60:63]
	v_mfma_f32_16x16x32_bf16 v[56:59], v[78:81], v[166:169], v[56:59]
	v_mfma_f32_16x16x32_bf16 v[44:47], v[70:73], v[174:177], v[44:47]
	v_mfma_f32_16x16x32_bf16 v[40:43], v[78:81], v[174:177], v[40:43]
	v_mfma_f32_16x16x32_bf16 v[28:31], v[70:73], v[182:185], v[28:31]
	v_mfma_f32_16x16x32_bf16 v[24:27], v[78:81], v[182:185], v[24:27]
	v_mfma_f32_16x16x32_bf16 v[12:15], v[70:73], v[206:209], v[12:15]
	v_mfma_f32_16x16x32_bf16 v[8:11], v[78:81], v[206:209], v[8:11]
	v_mfma_f32_16x16x32_bf16 v[52:55], v[82:85], v[162:165], v[52:55]
	v_mfma_f32_16x16x32_bf16 v[48:51], v[98:101], v[162:165], v[48:51]
	v_mfma_f32_16x16x32_bf16 v[36:39], v[82:85], v[170:173], v[36:39]
	v_mfma_f32_16x16x32_bf16 v[32:35], v[98:101], v[170:173], v[32:35]
	v_mfma_f32_16x16x32_bf16 v[20:23], v[82:85], v[178:181], v[20:23]
	v_mfma_f32_16x16x32_bf16 v[16:19], v[98:101], v[178:181], v[16:19]
	v_mfma_f32_16x16x32_bf16 v[4:7], v[82:85], v[186:189], v[4:7]
	v_mfma_f32_16x16x32_bf16 v[0:3], v[98:101], v[186:189], v[0:3]
	v_mfma_f32_16x16x32_bf16 v[52:55], v[90:93], v[166:169], v[52:55]
	v_mfma_f32_16x16x32_bf16 v[48:51], v[102:105], v[166:169], v[48:51]
	v_mfma_f32_16x16x32_bf16 v[36:39], v[90:93], v[174:177], v[36:39]
	v_mfma_f32_16x16x32_bf16 v[32:35], v[102:105], v[174:177], v[32:35]
	v_mfma_f32_16x16x32_bf16 v[20:23], v[90:93], v[182:185], v[20:23]
	v_mfma_f32_16x16x32_bf16 v[16:19], v[102:105], v[182:185], v[16:19]
	v_mfma_f32_16x16x32_bf16 v[4:7], v[90:93], v[206:209], v[4:7]
	v_mfma_f32_16x16x32_bf16 v[0:3], v[102:105], v[206:209], v[0:3]
	s_setprio 0
	s_barrier
	s_add_i32 s58, 0, 0x18000
	s_add_i32 s59, 0, 0x1c000
	v_add_u32_e32 v78, s58, v241
	v_add_u32_e32 v102, s59, v241
	ds_read_b128 v[66:69], v78
	ds_read_b128 v[70:73], v78 offset:1024
	ds_read_b128 v[74:77], v78 offset:2048
	ds_read_b128 v[78:81], v78 offset:3072
	ds_read_b128 v[82:85], v102
	ds_read_b128 v[90:93], v102 offset:1024
	ds_read_b128 v[98:101], v102 offset:2048
	ds_read_b128 v[102:105], v102 offset:3072
	s_add_u32 s34, s34, 0x100000
	s_addc_u32 s35, s35, 0
	s_mov_b32 m0, s66
	v_lshl_add_u64 v[218:219], s[34:35], 0, v[200:201]
	ds_read_b128 v[162:165], v242 offset:32768
	ds_read_b128 v[166:169], v242 offset:33792
	ds_read_b128 v[170:173], v242 offset:34816
	ds_read_b128 v[174:177], v242 offset:35840
	ds_read_b128 v[178:181], v242 offset:36864
	ds_read_b128 v[182:185], v242 offset:37888
	ds_read_b128 v[186:189], v242 offset:38912
	ds_read_b128 v[206:209], v242 offset:39936
	global_load_lds_dwordx4 v[218:219], off
	v_lshl_add_u64 v[218:219], s[34:35], 0, v[198:199]
	s_mov_b32 m0, s67
	s_nop 0
	global_load_lds_dwordx4 v[218:219], off
	s_waitcnt vmcnt(8)
	s_waitcnt lgkmcnt(0)
	s_barrier
	s_setprio 1
	s_waitcnt lgkmcnt(0)
	v_mfma_f32_16x16x32_bf16 v[158:161], v[66:69], v[162:165], v[158:161]
	v_mfma_f32_16x16x32_bf16 v[154:157], v[74:77], v[162:165], v[154:157]
	v_mfma_f32_16x16x32_bf16 v[142:145], v[66:69], v[170:173], v[142:145]
	v_mfma_f32_16x16x32_bf16 v[138:141], v[74:77], v[170:173], v[138:141]
	v_mfma_f32_16x16x32_bf16 v[126:129], v[66:69], v[178:181], v[126:129]
	v_mfma_f32_16x16x32_bf16 v[122:125], v[74:77], v[178:181], v[122:125]
	v_mfma_f32_16x16x32_bf16 v[110:113], v[66:69], v[186:189], v[110:113]
	v_mfma_f32_16x16x32_bf16 v[106:109], v[74:77], v[186:189], v[106:109]
	v_mfma_f32_16x16x32_bf16 v[158:161], v[70:73], v[166:169], v[158:161]
	v_mfma_f32_16x16x32_bf16 v[154:157], v[78:81], v[166:169], v[154:157]
	v_mfma_f32_16x16x32_bf16 v[142:145], v[70:73], v[174:177], v[142:145]
	v_mfma_f32_16x16x32_bf16 v[138:141], v[78:81], v[174:177], v[138:141]
	v_mfma_f32_16x16x32_bf16 v[126:129], v[70:73], v[182:185], v[126:129]
	v_mfma_f32_16x16x32_bf16 v[122:125], v[78:81], v[182:185], v[122:125]
	v_mfma_f32_16x16x32_bf16 v[110:113], v[70:73], v[206:209], v[110:113]
	v_mfma_f32_16x16x32_bf16 v[106:109], v[78:81], v[206:209], v[106:109]
	v_mfma_f32_16x16x32_bf16 v[150:153], v[82:85], v[162:165], v[150:153]
	v_mfma_f32_16x16x32_bf16 v[146:149], v[98:101], v[162:165], v[146:149]
	v_mfma_f32_16x16x32_bf16 v[134:137], v[82:85], v[170:173], v[134:137]
	v_mfma_f32_16x16x32_bf16 v[130:133], v[98:101], v[170:173], v[130:133]
	v_mfma_f32_16x16x32_bf16 v[118:121], v[82:85], v[178:181], v[118:121]
	v_mfma_f32_16x16x32_bf16 v[114:117], v[98:101], v[178:181], v[114:117]
	v_mfma_f32_16x16x32_bf16 v[94:97], v[82:85], v[186:189], v[94:97]
	v_mfma_f32_16x16x32_bf16 v[86:89], v[98:101], v[186:189], v[86:89]
	v_mfma_f32_16x16x32_bf16 v[150:153], v[90:93], v[166:169], v[150:153]
	v_mfma_f32_16x16x32_bf16 v[146:149], v[102:105], v[166:169], v[146:149]
	v_mfma_f32_16x16x32_bf16 v[134:137], v[90:93], v[174:177], v[134:137]
	v_mfma_f32_16x16x32_bf16 v[130:133], v[102:105], v[174:177], v[130:133]
	v_mfma_f32_16x16x32_bf16 v[118:121], v[90:93], v[182:185], v[118:121]
	v_mfma_f32_16x16x32_bf16 v[114:117], v[102:105], v[182:185], v[114:117]
	v_mfma_f32_16x16x32_bf16 v[94:97], v[90:93], v[206:209], v[94:97]
	v_mfma_f32_16x16x32_bf16 v[86:89], v[102:105], v[206:209], v[86:89]
	s_setprio 0
	s_barrier
	s_add_i32 s34, s58, s60
	v_lshl_add_u64 v[210:211], v[210:211], 0, s[30:31]
	s_mov_b32 m0, s34
	ds_read_b128 v[162:165], v242 offset:49152
	ds_read_b128 v[166:169], v242 offset:50176
	ds_read_b128 v[170:173], v242 offset:51200
	ds_read_b128 v[174:177], v242 offset:52224
	ds_read_b128 v[178:181], v242 offset:53248
	ds_read_b128 v[182:185], v242 offset:54272
	ds_read_b128 v[186:189], v242 offset:55296
	ds_read_b128 v[206:209], v242 offset:56320
	global_load_lds_dwordx4 v[210:211], off
	s_add_i32 m0, s34, 0x2000
	s_add_u32 s8, s8, 0x100080
	v_lshl_add_u64 v[210:211], v[212:213], 0, s[30:31]
	s_addc_u32 s9, s9, 0
	s_add_i32 s34, s59, s60
	global_load_lds_dwordx4 v[210:211], off
	v_lshl_add_u64 v[210:211], s[8:9], 0, v[64:65]
	s_mov_b32 m0, s34
	s_nop 0
	global_load_lds_dwordx4 v[210:211], off
	v_lshl_add_u64 v[210:211], s[8:9], 0, v[196:197]
	s_add_i32 m0, s34, 0x2000
	s_nop 0
	global_load_lds_dwordx4 v[210:211], off
	v_lshl_add_u64 v[210:211], v[214:215], 0, s[30:31]
	s_mov_b32 m0, s86
	s_nop 0
	global_load_lds_dwordx4 v[210:211], off
	v_lshl_add_u64 v[210:211], v[216:217], 0, s[30:31]
	s_mov_b32 m0, s87
	s_nop 0
	global_load_lds_dwordx4 v[210:211], off
	s_waitcnt vmcnt(8)
	s_waitcnt lgkmcnt(0)
	s_barrier
	s_setprio 1
	s_waitcnt lgkmcnt(0)
	v_mfma_f32_16x16x32_bf16 v[60:63], v[66:69], v[162:165], v[60:63]
	v_mfma_f32_16x16x32_bf16 v[56:59], v[74:77], v[162:165], v[56:59]
	v_mfma_f32_16x16x32_bf16 v[44:47], v[66:69], v[170:173], v[44:47]
	v_mfma_f32_16x16x32_bf16 v[40:43], v[74:77], v[170:173], v[40:43]
	v_mfma_f32_16x16x32_bf16 v[28:31], v[66:69], v[178:181], v[28:31]
	v_mfma_f32_16x16x32_bf16 v[24:27], v[74:77], v[178:181], v[24:27]
	v_mfma_f32_16x16x32_bf16 v[12:15], v[66:69], v[186:189], v[12:15]
	v_mfma_f32_16x16x32_bf16 v[8:11], v[74:77], v[186:189], v[8:11]
	v_mfma_f32_16x16x32_bf16 v[60:63], v[70:73], v[166:169], v[60:63]
	v_mfma_f32_16x16x32_bf16 v[56:59], v[78:81], v[166:169], v[56:59]
	v_mfma_f32_16x16x32_bf16 v[44:47], v[70:73], v[174:177], v[44:47]
	v_mfma_f32_16x16x32_bf16 v[40:43], v[78:81], v[174:177], v[40:43]
	v_mfma_f32_16x16x32_bf16 v[28:31], v[70:73], v[182:185], v[28:31]
	v_mfma_f32_16x16x32_bf16 v[24:27], v[78:81], v[182:185], v[24:27]
	v_mfma_f32_16x16x32_bf16 v[12:15], v[70:73], v[206:209], v[12:15]
	v_mfma_f32_16x16x32_bf16 v[8:11], v[78:81], v[206:209], v[8:11]
	v_mfma_f32_16x16x32_bf16 v[52:55], v[82:85], v[162:165], v[52:55]
	v_mfma_f32_16x16x32_bf16 v[48:51], v[98:101], v[162:165], v[48:51]
	v_mfma_f32_16x16x32_bf16 v[36:39], v[82:85], v[170:173], v[36:39]
	v_mfma_f32_16x16x32_bf16 v[32:35], v[98:101], v[170:173], v[32:35]
	v_mfma_f32_16x16x32_bf16 v[20:23], v[82:85], v[178:181], v[20:23]
	v_mfma_f32_16x16x32_bf16 v[16:19], v[98:101], v[178:181], v[16:19]
	v_mfma_f32_16x16x32_bf16 v[4:7], v[82:85], v[186:189], v[4:7]
	v_mfma_f32_16x16x32_bf16 v[0:3], v[98:101], v[186:189], v[0:3]
	v_mfma_f32_16x16x32_bf16 v[52:55], v[90:93], v[166:169], v[52:55]
	v_mfma_f32_16x16x32_bf16 v[48:51], v[102:105], v[166:169], v[48:51]
	v_mfma_f32_16x16x32_bf16 v[36:39], v[90:93], v[174:177], v[36:39]
	v_mfma_f32_16x16x32_bf16 v[32:35], v[102:105], v[174:177], v[32:35]
	v_mfma_f32_16x16x32_bf16 v[20:23], v[90:93], v[182:185], v[20:23]
	v_mfma_f32_16x16x32_bf16 v[16:19], v[102:105], v[182:185], v[16:19]
	v_mfma_f32_16x16x32_bf16 v[4:7], v[90:93], v[206:209], v[4:7]
	v_mfma_f32_16x16x32_bf16 v[0:3], v[102:105], v[206:209], v[0:3]
	s_setprio 0
	s_barrier
	s_add_i32 vcc_hi, vcc_hi, 2
	s_add_u32 s96, s96, 0x100
	s_addc_u32 vcc_lo, vcc_lo, 0
	s_add_u32 s6, s6, 0x100
	s_addc_u32 s7, s7, 0
	s_cmp_gt_u32 vcc_hi, 61
	s_cbranch_scc0 .LBB0_2178
	s_and_b64 vcc, exec, s[12:13]
	s_cbranch_vccz .LBB0_2181
	s_barrier
